# GEMM K-loops: redundant adjacent s_setprio 0/1 pairs between MFMAs removed (on top of v019)
# baseline (speedup 1.0000x reference)
; #define PG8_STAGE(bufoff, gbase, voff) do { _Pragma("unroll") for (int _i = 0; _i < 2; ++_i) \
;         __builtin_amdgcn_global_load_lds((const unsigned*)((const char*)(gbase) + (voff)[_i]), (PG8_LAS unsigned*)(lds + (bufoff) + ldsw + _i * 8192), 16, 0, 0); } while (0)
; #define PG8_LDA(dst, b, h) do { _Pragma("unroll") for (int m = 0; m < 4; ++m) _Pragma("unroll") for (int k = 0; k < 2; ++k) dst[m][k] = *(const PG8_LAS bf16x8*)(lds + PG8_SA(b, h) + aoff + m * 2048 + k * 1024); } while (0)
; #define PG8_LDB(dst, b, h) do { _Pragma("unroll") for (int n = 0; n < 2; ++n) _Pragma("unroll") for (int k = 0; k < 2; ++k) dst[n][k] = *(const PG8_LAS bf16x8*)(lds + PG8_SB(b, h) + boff + n * 2048 + k * 1024); } while (0)
; #define PG8_MMA(ai, bj, At, Bt) do { __builtin_amdgcn_s_setprio(1); _Pragma("unroll") for (int m = 0; m < 4; ++m) _Pragma("unroll") for (int n = 0; n < 2; ++n) _Pragma("unroll") for (int k = 0; k < 2; ++k) \
;         acc[ai][bj][m][n] = __builtin_amdgcn_mfma_f32_16x16x32_bf16(Bt[n][k], At[m][k], acc[ai][bj][m][n], 0, 0, 0); __builtin_amdgcn_s_setprio(0); } while (0)
; #define PG8_BAR __builtin_amdgcn_s_barrier()
; template <class Epi, class Sched, bool ALIGN_EPI = false, bool SP2 = false>
; __device__ __forceinline__ void gemm_phase(PG8_LAS unsigned char* lds, const Gemm g, const Sched& S, const Epi& E) {
;     ...
;         const bool has_next = S.next(ui + 1, nxt);
;         const char* nA = has_next ? (const char*)g.A + (size_t)nxt.pm * tstep : cA; const char* nB = has_next ? (const char*)g.Bt + (size_t)nxt.pn * tstep : cB;
;         for (int t = 0; t < nt; t += 2) {
;             const bool last = (t == nt - 2);
;             const char* a1 = cA + (size_t)(t + 1) * kstep;
;             const char* a2 = last ? nA : cA + (size_t)(t + 2) * kstep; const char* b2 = last ? nB : cB + (size_t)(t + 2) * kstep;
;             const char* a3 = a2 + kstep; const char* b3 = b2 + kstep;
;             if (last && has_next) S.a_ready(nxt);
;             if constexpr (SP2) {
;             PG8_LDB(B0, 0, 0); PG8_LDB(B1, 0, 1); PG8_SCHED; PG8_LDA(At, 0, 0); PG8_STAGE(PG8_SA(1, 1), a1 + hstep, voffA);
;             PG8_WAIT_V(8); PG8_WAIT_L(0); PG8_BAR; PG8_MMA(0, 0, At, B0); PG8_MMA(0, 1, At, B1); PG8_BAR; PG8_SCHED;
;             PG8_LDA(At, 0, 1); PG8_STAGE(PG8_SB(0, 0), b2, voffB); PG8_STAGE(PG8_SB(0, 1), b2 + hstep, voffB); PG8_STAGE(PG8_SA(0, 0), a2, voffA);
.LBB0_145:
	s_add_u32 s46, s90, 0xfffc0080
	s_addc_u32 s47, s91, -1
	s_add_i32 s66, 0, 0x10000
	s_cmp_eq_u32 s65, 12
	s_cselect_b32 s51, s31, s47
	s_cselect_b32 s50, s43, s46
	v_add_u32_e32 v142, s66, v145
	s_cselect_b32 s47, s29, s64
	s_cselect_b32 s46, s62, s63
	s_add_i32 s68, 0, 0x14000
	ds_read_b128 v[150:153], v142
	ds_read_b128 v[154:157], v142 offset:1024
	ds_read_b128 v[158:161], v142 offset:2048
	ds_read_b128 v[162:165], v142 offset:3072
	v_add_u32_e32 v142, s68, v145
	ds_read_b128 v[166:169], v142
	ds_read_b128 v[170:173], v142 offset:1024
	ds_read_b128 v[174:177], v142 offset:2048
	ds_read_b128 v[178:181], v142 offset:3072
	v_lshl_add_u64 v[142:143], s[90:91], 0, v[138:139]
	s_add_i32 m0, s52, 0xc000
	ds_read_b128 v[182:185], v149
	ds_read_b128 v[186:189], v149 offset:1024
	ds_read_b128 v[190:193], v149 offset:2048
	ds_read_b128 v[204:207], v149 offset:3072
	ds_read_b128 v[208:211], v149 offset:4096
	ds_read_b128 v[212:215], v149 offset:5120
	ds_read_b128 v[216:219], v149 offset:6144
	ds_read_b128 v[220:223], v149 offset:7168
	global_load_lds_dwordx4 v[142:143], off
	v_lshl_add_u64 v[142:143], s[90:91], 0, v[140:141]
	s_add_i32 m0, s52, 0xe000
	s_nop 0
	global_load_lds_dwordx4 v[142:143], off
	s_waitcnt vmcnt(8)
	s_waitcnt lgkmcnt(0)
	s_barrier
	s_setprio 1
	s_waitcnt lgkmcnt(0)
	v_mfma_f32_16x16x32_bf16 v[126:129], v[150:153], v[182:185], v[126:129]
	v_mfma_f32_16x16x32_bf16 v[122:125], v[158:161], v[182:185], v[122:125]
	v_mfma_f32_16x16x32_bf16 v[114:117], v[150:153], v[190:193], v[114:117]
	v_mfma_f32_16x16x32_bf16 v[106:109], v[158:161], v[190:193], v[106:109]
	v_mfma_f32_16x16x32_bf16 v[98:101], v[150:153], v[208:211], v[98:101]
	v_mfma_f32_16x16x32_bf16 v[90:93], v[158:161], v[208:211], v[90:93]
	v_mfma_f32_16x16x32_bf16 v[82:85], v[150:153], v[216:219], v[82:85]
	v_mfma_f32_16x16x32_bf16 v[74:77], v[158:161], v[216:219], v[74:77]
	v_mfma_f32_16x16x32_bf16 v[126:129], v[154:157], v[186:189], v[126:129]
	v_mfma_f32_16x16x32_bf16 v[122:125], v[162:165], v[186:189], v[122:125]
	v_mfma_f32_16x16x32_bf16 v[114:117], v[154:157], v[204:207], v[114:117]
	v_mfma_f32_16x16x32_bf16 v[106:109], v[162:165], v[204:207], v[106:109]
	v_mfma_f32_16x16x32_bf16 v[98:101], v[154:157], v[212:215], v[98:101]
	v_mfma_f32_16x16x32_bf16 v[90:93], v[162:165], v[212:215], v[90:93]
	v_mfma_f32_16x16x32_bf16 v[82:85], v[154:157], v[220:223], v[82:85]
	v_mfma_f32_16x16x32_bf16 v[74:77], v[162:165], v[220:223], v[74:77]
	v_mfma_f32_16x16x32_bf16 v[118:121], v[166:169], v[182:185], v[118:121]
	v_mfma_f32_16x16x32_bf16 v[110:113], v[174:177], v[182:185], v[110:113]
	v_mfma_f32_16x16x32_bf16 v[102:105], v[166:169], v[190:193], v[102:105]
	v_mfma_f32_16x16x32_bf16 v[94:97], v[174:177], v[190:193], v[94:97]
	v_mfma_f32_16x16x32_bf16 v[86:89], v[166:169], v[208:211], v[86:89]
	v_mfma_f32_16x16x32_bf16 v[78:81], v[174:177], v[208:211], v[78:81]
	v_mfma_f32_16x16x32_bf16 v[70:73], v[166:169], v[216:219], v[70:73]
	v_mfma_f32_16x16x32_bf16 v[66:69], v[174:177], v[216:219], v[66:69]
	v_mfma_f32_16x16x32_bf16 v[118:121], v[170:173], v[186:189], v[118:121]
	v_mfma_f32_16x16x32_bf16 v[110:113], v[178:181], v[186:189], v[110:113]
	v_mfma_f32_16x16x32_bf16 v[102:105], v[170:173], v[204:207], v[102:105]
	v_mfma_f32_16x16x32_bf16 v[94:97], v[178:181], v[204:207], v[94:97]
	v_mfma_f32_16x16x32_bf16 v[86:89], v[170:173], v[212:215], v[86:89]
	v_mfma_f32_16x16x32_bf16 v[78:81], v[178:181], v[212:215], v[78:81]
	v_mfma_f32_16x16x32_bf16 v[70:73], v[170:173], v[220:223], v[70:73]
	v_mfma_f32_16x16x32_bf16 v[66:69], v[178:181], v[220:223], v[66:69]
	s_setprio 0
	s_barrier
	s_add_i32 s66, s66, s45
	v_lshl_add_u64 v[142:143], s[46:47], 0, v[134:135]
	s_mov_b32 m0, s66
	ds_read_b128 v[182:185], v149 offset:16384
	ds_read_b128 v[186:189], v149 offset:17408
	ds_read_b128 v[190:193], v149 offset:18432
	ds_read_b128 v[204:207], v149 offset:19456
	ds_read_b128 v[208:211], v149 offset:20480
	ds_read_b128 v[212:215], v149 offset:21504
	ds_read_b128 v[216:219], v149 offset:22528
	ds_read_b128 v[220:223], v149 offset:23552
	global_load_lds_dwordx4 v[142:143], off
	s_add_i32 m0, s66, 0x2000
	s_add_u32 s66, s46, 0x40000
	v_lshl_add_u64 v[146:147], s[46:47], 0, v[130:131]
	s_addc_u32 s67, s47, 0
	s_add_i32 s68, s68, s45
	global_load_lds_dwordx4 v[146:147], off
	v_lshl_add_u64 v[224:225], s[66:67], 0, v[134:135]
	s_mov_b32 m0, s68
	v_lshl_add_u64 v[226:227], s[50:51], 0, v[132:133]
	global_load_lds_dwordx4 v[224:225], off
	v_lshl_add_u64 v[224:225], s[66:67], 0, v[130:131]
	s_add_i32 m0, s68, 0x2000
	s_nop 0
	global_load_lds_dwordx4 v[224:225], off
	v_lshl_add_u64 v[224:225], s[50:51], 0, v[136:137]
	s_mov_b32 m0, s52
	s_nop 0
	global_load_lds_dwordx4 v[224:225], off
	s_mov_b32 m0, s53
	s_nop 0
	global_load_lds_dwordx4 v[226:227], off
	s_waitcnt vmcnt(8)
	s_waitcnt lgkmcnt(0)
	s_barrier
; #define PG8_STAGE(bufoff, gbase, voff) do { _Pragma("unroll") for (int _i = 0; _i < 2; ++_i) \
;         __builtin_amdgcn_global_load_lds((const unsigned*)((const char*)(gbase) + (voff)[_i]), (PG8_LAS unsigned*)(lds + (bufoff) + ldsw + _i * 8192), 16, 0, 0); } while (0)
; #define PG8_LDA(dst, b, h) do { _Pragma("unroll") for (int m = 0; m < 4; ++m) _Pragma("unroll") for (int k = 0; k < 2; ++k) dst[m][k] = *(const PG8_LAS bf16x8*)(lds + PG8_SA(b, h) + aoff + m * 2048 + k * 1024); } while (0)
; #define PG8_LDB(dst, b, h) do { _Pragma("unroll") for (int n = 0; n < 2; ++n) _Pragma("unroll") for (int k = 0; k < 2; ++k) dst[n][k] = *(const PG8_LAS bf16x8*)(lds + PG8_SB(b, h) + boff + n * 2048 + k * 1024); } while (0)
; #define PG8_MMA(ai, bj, At, Bt) do { __builtin_amdgcn_s_setprio(1); _Pragma("unroll") for (int m = 0; m < 4; ++m) _Pragma("unroll") for (int n = 0; n < 2; ++n) _Pragma("unroll") for (int k = 0; k < 2; ++k) \
;         acc[ai][bj][m][n] = __builtin_amdgcn_mfma_f32_16x16x32_bf16(Bt[n][k], At[m][k], acc[ai][bj][m][n], 0, 0, 0); __builtin_amdgcn_s_setprio(0); } while (0)
; #define PG8_WAIT_V(n) asm volatile("s_waitcnt vmcnt(" #n ")" ::: "memory")
; #define PG8_WAIT_L(n) asm volatile("s_waitcnt lgkmcnt(" #n ")" ::: "memory")
; #define PG8_BAR __builtin_amdgcn_s_barrier()
; #define PG8_SCHED __builtin_amdgcn_sched_barrier(0)
; template <class Epi, class Sched, bool ALIGN_EPI = false, bool SP2 = false>
; __device__ __forceinline__ void gemm_phase(PG8_LAS unsigned char* lds, const Gemm g, const Sched& S, const Epi& E) {
;     ...
;             PG8_WAIT_V(8); PG8_WAIT_L(0); PG8_BAR; PG8_MMA(1, 0, At, B0); PG8_MMA(1, 1, At, B1); PG8_BAR; PG8_SCHED;
;             PG8_LDB(B0, 1, 0); PG8_LDB(B1, 1, 1); PG8_SCHED; PG8_LDA(At, 1, 0); PG8_STAGE(PG8_SA(0, 1), a2 + hstep, voffA);
;             PG8_WAIT_V(8); PG8_WAIT_L(0); PG8_BAR; PG8_MMA(0, 0, At, B0); PG8_MMA(0, 1, At, B1); PG8_BAR; PG8_SCHED;
	s_setprio 1
	s_waitcnt lgkmcnt(0)
	v_mfma_f32_16x16x32_bf16 v[62:65], v[150:153], v[182:185], v[62:65]
	v_mfma_f32_16x16x32_bf16 v[58:61], v[158:161], v[182:185], v[58:61]
	v_mfma_f32_16x16x32_bf16 v[50:53], v[150:153], v[190:193], v[50:53]
	v_mfma_f32_16x16x32_bf16 v[42:45], v[158:161], v[190:193], v[42:45]
	v_mfma_f32_16x16x32_bf16 v[34:37], v[150:153], v[208:211], v[34:37]
	v_mfma_f32_16x16x32_bf16 v[24:27], v[158:161], v[208:211], v[24:27]
	v_mfma_f32_16x16x32_bf16 v[16:19], v[150:153], v[216:219], v[16:19]
	v_mfma_f32_16x16x32_bf16 v[8:11], v[158:161], v[216:219], v[8:11]
	v_mfma_f32_16x16x32_bf16 v[62:65], v[154:157], v[186:189], v[62:65]
	v_mfma_f32_16x16x32_bf16 v[58:61], v[162:165], v[186:189], v[58:61]
	v_mfma_f32_16x16x32_bf16 v[50:53], v[154:157], v[204:207], v[50:53]
	v_mfma_f32_16x16x32_bf16 v[42:45], v[162:165], v[204:207], v[42:45]
	v_mfma_f32_16x16x32_bf16 v[34:37], v[154:157], v[212:215], v[34:37]
	v_mfma_f32_16x16x32_bf16 v[24:27], v[162:165], v[212:215], v[24:27]
	v_mfma_f32_16x16x32_bf16 v[16:19], v[154:157], v[220:223], v[16:19]
	v_mfma_f32_16x16x32_bf16 v[8:11], v[162:165], v[220:223], v[8:11]
	v_mfma_f32_16x16x32_bf16 v[54:57], v[166:169], v[182:185], v[54:57]
	v_mfma_f32_16x16x32_bf16 v[46:49], v[174:177], v[182:185], v[46:49]
	v_mfma_f32_16x16x32_bf16 v[38:41], v[166:169], v[190:193], v[38:41]
	v_mfma_f32_16x16x32_bf16 v[28:31], v[174:177], v[190:193], v[28:31]
	v_mfma_f32_16x16x32_bf16 v[20:23], v[166:169], v[208:211], v[20:23]
	v_mfma_f32_16x16x32_bf16 v[12:15], v[174:177], v[208:211], v[12:15]
	v_mfma_f32_16x16x32_bf16 v[4:7], v[166:169], v[216:219], v[4:7]
	v_mfma_f32_16x16x32_bf16 v[0:3], v[174:177], v[216:219], v[0:3]
	v_mfma_f32_16x16x32_bf16 v[54:57], v[170:173], v[186:189], v[54:57]
	v_mfma_f32_16x16x32_bf16 v[46:49], v[178:181], v[186:189], v[46:49]
	v_mfma_f32_16x16x32_bf16 v[38:41], v[170:173], v[204:207], v[38:41]
	v_mfma_f32_16x16x32_bf16 v[28:31], v[178:181], v[204:207], v[28:31]
	v_mfma_f32_16x16x32_bf16 v[20:23], v[170:173], v[212:215], v[20:23]
	v_mfma_f32_16x16x32_bf16 v[12:15], v[178:181], v[212:215], v[12:15]
	v_mfma_f32_16x16x32_bf16 v[4:7], v[170:173], v[220:223], v[4:7]
	v_mfma_f32_16x16x32_bf16 v[0:3], v[178:181], v[220:223], v[0:3]
	s_setprio 0
	s_barrier
	s_add_i32 s66, 0, 0x18000
	v_add_u32_e32 v144, s66, v145
	s_add_i32 s67, 0, 0x1c000
	ds_read_b128 v[150:153], v144
	ds_read_b128 v[154:157], v144 offset:1024
	ds_read_b128 v[158:161], v144 offset:2048
	ds_read_b128 v[162:165], v144 offset:3072
	v_add_u32_e32 v144, s67, v145
	ds_read_b128 v[166:169], v144
	ds_read_b128 v[170:173], v144 offset:1024
	ds_read_b128 v[174:177], v144 offset:2048
	ds_read_b128 v[178:181], v144 offset:3072
	s_add_u32 s50, s50, 0x40000
	s_addc_u32 s51, s51, 0
	s_mov_b32 m0, s55
	v_lshl_add_u64 v[238:239], s[50:51], 0, v[136:137]
	ds_read_b128 v[182:185], v149 offset:32768
	ds_read_b128 v[186:189], v149 offset:33792
	ds_read_b128 v[190:193], v149 offset:34816
	ds_read_b128 v[204:207], v149 offset:35840
	ds_read_b128 v[208:211], v149 offset:36864
	ds_read_b128 v[212:215], v149 offset:37888
	ds_read_b128 v[216:219], v149 offset:38912
	ds_read_b128 v[220:223], v149 offset:39936
	global_load_lds_dwordx4 v[238:239], off
	v_lshl_add_u64 v[238:239], s[50:51], 0, v[132:133]
	s_mov_b32 m0, s56
	s_nop 0
	global_load_lds_dwordx4 v[238:239], off
	s_waitcnt vmcnt(8)
	s_waitcnt lgkmcnt(0)
	s_barrier
	s_setprio 1
	s_waitcnt lgkmcnt(0)
	v_mfma_f32_16x16x32_bf16 v[126:129], v[150:153], v[182:185], v[126:129]
	v_mfma_f32_16x16x32_bf16 v[122:125], v[158:161], v[182:185], v[122:125]
	v_mfma_f32_16x16x32_bf16 v[114:117], v[150:153], v[190:193], v[114:117]
	v_mfma_f32_16x16x32_bf16 v[106:109], v[158:161], v[190:193], v[106:109]
	v_mfma_f32_16x16x32_bf16 v[98:101], v[150:153], v[208:211], v[98:101]
	v_mfma_f32_16x16x32_bf16 v[90:93], v[158:161], v[208:211], v[90:93]
	v_mfma_f32_16x16x32_bf16 v[82:85], v[150:153], v[216:219], v[82:85]
	v_mfma_f32_16x16x32_bf16 v[74:77], v[158:161], v[216:219], v[74:77]
	v_mfma_f32_16x16x32_bf16 v[126:129], v[154:157], v[186:189], v[126:129]
	v_mfma_f32_16x16x32_bf16 v[122:125], v[162:165], v[186:189], v[122:125]
	v_mfma_f32_16x16x32_bf16 v[114:117], v[154:157], v[204:207], v[114:117]
	v_mfma_f32_16x16x32_bf16 v[106:109], v[162:165], v[204:207], v[106:109]
	v_mfma_f32_16x16x32_bf16 v[98:101], v[154:157], v[212:215], v[98:101]
	v_mfma_f32_16x16x32_bf16 v[90:93], v[162:165], v[212:215], v[90:93]
	v_mfma_f32_16x16x32_bf16 v[82:85], v[154:157], v[220:223], v[82:85]
	v_mfma_f32_16x16x32_bf16 v[74:77], v[162:165], v[220:223], v[74:77]
	v_mfma_f32_16x16x32_bf16 v[118:121], v[166:169], v[182:185], v[118:121]
	v_mfma_f32_16x16x32_bf16 v[110:113], v[174:177], v[182:185], v[110:113]
	v_mfma_f32_16x16x32_bf16 v[102:105], v[166:169], v[190:193], v[102:105]
	v_mfma_f32_16x16x32_bf16 v[94:97], v[174:177], v[190:193], v[94:97]
	v_mfma_f32_16x16x32_bf16 v[86:89], v[166:169], v[208:211], v[86:89]
	v_mfma_f32_16x16x32_bf16 v[78:81], v[174:177], v[208:211], v[78:81]
	v_mfma_f32_16x16x32_bf16 v[70:73], v[166:169], v[216:219], v[70:73]
	v_mfma_f32_16x16x32_bf16 v[66:69], v[174:177], v[216:219], v[66:69]
	v_mfma_f32_16x16x32_bf16 v[118:121], v[170:173], v[186:189], v[118:121]
	v_mfma_f32_16x16x32_bf16 v[110:113], v[178:181], v[186:189], v[110:113]
	v_mfma_f32_16x16x32_bf16 v[102:105], v[170:173], v[204:207], v[102:105]
	v_mfma_f32_16x16x32_bf16 v[94:97], v[178:181], v[204:207], v[94:97]
	v_mfma_f32_16x16x32_bf16 v[86:89], v[170:173], v[212:215], v[86:89]
	v_mfma_f32_16x16x32_bf16 v[78:81], v[178:181], v[212:215], v[78:81]
	v_mfma_f32_16x16x32_bf16 v[70:73], v[170:173], v[220:223], v[70:73]
	v_mfma_f32_16x16x32_bf16 v[66:69], v[178:181], v[220:223], v[66:69]
	s_setprio 0
	s_barrier
; #define PG8_STAGE(bufoff, gbase, voff) do { _Pragma("unroll") for (int _i = 0; _i < 2; ++_i) \
;         __builtin_amdgcn_global_load_lds((const unsigned*)((const char*)(gbase) + (voff)[_i]), (PG8_LAS unsigned*)(lds + (bufoff) + ldsw + _i * 8192), 16, 0, 0); } while (0)
; #define PG8_LDA(dst, b, h) do { _Pragma("unroll") for (int m = 0; m < 4; ++m) _Pragma("unroll") for (int k = 0; k < 2; ++k) dst[m][k] = *(const PG8_LAS bf16x8*)(lds + PG8_SA(b, h) + aoff + m * 2048 + k * 1024); } while (0)
; #define PG8_MMA(ai, bj, At, Bt) do { __builtin_amdgcn_s_setprio(1); _Pragma("unroll") for (int m = 0; m < 4; ++m) _Pragma("unroll") for (int n = 0; n < 2; ++n) _Pragma("unroll") for (int k = 0; k < 2; ++k) \
;         acc[ai][bj][m][n] = __builtin_amdgcn_mfma_f32_16x16x32_bf16(Bt[n][k], At[m][k], acc[ai][bj][m][n], 0, 0, 0); __builtin_amdgcn_s_setprio(0); } while (0)
; #define PG8_WAIT_V(n) asm volatile("s_waitcnt vmcnt(" #n ")" ::: "memory")
; #define PG8_WAIT_L(n) asm volatile("s_waitcnt lgkmcnt(" #n ")" ::: "memory")
; #define PG8_BAR __builtin_amdgcn_s_barrier()
; #define PG8_SCHED __builtin_amdgcn_sched_barrier(0)
; template <class Epi, class Sched, bool ALIGN_EPI = false, bool SP2 = false>
; __device__ __forceinline__ void gemm_phase(PG8_LAS unsigned char* lds, const Gemm g, const Sched& S, const Epi& E) {
;     ...
;             PG8_LDA(At, 1, 1); PG8_STAGE(PG8_SB(1, 0), b3, voffB); PG8_STAGE(PG8_SB(1, 1), b3 + hstep, voffB); PG8_STAGE(PG8_SA(1, 0), a3, voffA);
;             PG8_WAIT_V(8); PG8_WAIT_L(0); PG8_BAR; PG8_MMA(1, 0, At, B0); PG8_MMA(1, 1, At, B1); PG8_BAR; PG8_SCHED;
	s_add_i32 s50, s66, s45
	v_lshl_add_u64 v[142:143], v[142:143], 0, s[8:9]
	s_mov_b32 m0, s50
	ds_read_b128 v[182:185], v149 offset:49152
	ds_read_b128 v[186:189], v149 offset:50176
	ds_read_b128 v[190:193], v149 offset:51200
	ds_read_b128 v[204:207], v149 offset:52224
	ds_read_b128 v[208:211], v149 offset:53248
	ds_read_b128 v[212:215], v149 offset:54272
	ds_read_b128 v[216:219], v149 offset:55296
	ds_read_b128 v[220:223], v149 offset:56320
	global_load_lds_dwordx4 v[142:143], off
	s_add_i32 m0, s50, 0x2000
	s_add_u32 s46, s46, 0x40080
	v_lshl_add_u64 v[142:143], v[146:147], 0, s[8:9]
	s_addc_u32 s47, s47, 0
	s_add_i32 s50, s67, s45
	global_load_lds_dwordx4 v[142:143], off
	v_lshl_add_u64 v[142:143], s[46:47], 0, v[134:135]
	s_mov_b32 m0, s50
	s_nop 0
	global_load_lds_dwordx4 v[142:143], off
	v_lshl_add_u64 v[142:143], s[46:47], 0, v[130:131]
	s_add_i32 m0, s50, 0x2000
	s_nop 0
	global_load_lds_dwordx4 v[142:143], off
	v_lshl_add_u64 v[142:143], v[224:225], 0, s[8:9]
	s_mov_b32 m0, s58
	s_nop 0
	global_load_lds_dwordx4 v[142:143], off
	v_lshl_add_u64 v[142:143], v[226:227], 0, s[8:9]
	s_mov_b32 m0, s59
	s_nop 0
	global_load_lds_dwordx4 v[142:143], off
	s_waitcnt vmcnt(8)
	s_waitcnt lgkmcnt(0)
	s_barrier
	s_setprio 1
	s_waitcnt lgkmcnt(0)
	v_mfma_f32_16x16x32_bf16 v[62:65], v[150:153], v[182:185], v[62:65]
	v_mfma_f32_16x16x32_bf16 v[58:61], v[158:161], v[182:185], v[58:61]
	v_mfma_f32_16x16x32_bf16 v[50:53], v[150:153], v[190:193], v[50:53]
	v_mfma_f32_16x16x32_bf16 v[42:45], v[158:161], v[190:193], v[42:45]
	v_mfma_f32_16x16x32_bf16 v[34:37], v[150:153], v[208:211], v[34:37]
	v_mfma_f32_16x16x32_bf16 v[24:27], v[158:161], v[208:211], v[24:27]
	v_mfma_f32_16x16x32_bf16 v[16:19], v[150:153], v[216:219], v[16:19]
	v_mfma_f32_16x16x32_bf16 v[8:11], v[158:161], v[216:219], v[8:11]
	v_mfma_f32_16x16x32_bf16 v[62:65], v[154:157], v[186:189], v[62:65]
	v_mfma_f32_16x16x32_bf16 v[58:61], v[162:165], v[186:189], v[58:61]
	v_mfma_f32_16x16x32_bf16 v[50:53], v[154:157], v[204:207], v[50:53]
	v_mfma_f32_16x16x32_bf16 v[42:45], v[162:165], v[204:207], v[42:45]
	v_mfma_f32_16x16x32_bf16 v[34:37], v[154:157], v[212:215], v[34:37]
	v_mfma_f32_16x16x32_bf16 v[24:27], v[162:165], v[212:215], v[24:27]
	v_mfma_f32_16x16x32_bf16 v[16:19], v[154:157], v[220:223], v[16:19]
	v_mfma_f32_16x16x32_bf16 v[8:11], v[162:165], v[220:223], v[8:11]
	v_mfma_f32_16x16x32_bf16 v[54:57], v[166:169], v[182:185], v[54:57]
	v_mfma_f32_16x16x32_bf16 v[46:49], v[174:177], v[182:185], v[46:49]
	v_mfma_f32_16x16x32_bf16 v[38:41], v[166:169], v[190:193], v[38:41]
	v_mfma_f32_16x16x32_bf16 v[28:31], v[174:177], v[190:193], v[28:31]
	v_mfma_f32_16x16x32_bf16 v[20:23], v[166:169], v[208:211], v[20:23]
	v_mfma_f32_16x16x32_bf16 v[12:15], v[174:177], v[208:211], v[12:15]
	v_mfma_f32_16x16x32_bf16 v[4:7], v[166:169], v[216:219], v[4:7]
	v_mfma_f32_16x16x32_bf16 v[0:3], v[174:177], v[216:219], v[0:3]
	v_mfma_f32_16x16x32_bf16 v[54:57], v[170:173], v[186:189], v[54:57]
	v_mfma_f32_16x16x32_bf16 v[46:49], v[178:181], v[186:189], v[46:49]
	v_mfma_f32_16x16x32_bf16 v[38:41], v[170:173], v[204:207], v[38:41]
	v_mfma_f32_16x16x32_bf16 v[28:31], v[178:181], v[204:207], v[28:31]
	v_mfma_f32_16x16x32_bf16 v[20:23], v[170:173], v[212:215], v[20:23]
	v_mfma_f32_16x16x32_bf16 v[12:15], v[178:181], v[212:215], v[12:15]
	v_mfma_f32_16x16x32_bf16 v[4:7], v[170:173], v[220:223], v[4:7]
	v_mfma_f32_16x16x32_bf16 v[0:3], v[178:181], v[220:223], v[0:3]
	s_setprio 0
	s_barrier
	s_add_i32 s65, s65, 2
	s_add_u32 s90, s90, 0x100
	s_addc_u32 s91, s91, 0
	s_add_u32 s63, s63, 0x100
	s_addc_u32 s64, s64, 0
	s_cmp_gt_u32 s65, 13
	s_cbranch_scc0 .LBB0_145
	s_and_b64 vcc, exec, s[26:27]
	s_cbranch_vccz .LBB0_148
	s_barrier

; #define PG8_STAGE(bufoff, gbase, voff) do { _Pragma("unroll") for (int _i = 0; _i < 2; ++_i) \
;         __builtin_amdgcn_global_load_lds((const unsigned*)((const char*)(gbase) + (voff)[_i]), (PG8_LAS unsigned*)(lds + (bufoff) + ldsw + _i * 8192), 16, 0, 0); } while (0)
; #define PG8_LDA(dst, b, h) do { _Pragma("unroll") for (int m = 0; m < 4; ++m) _Pragma("unroll") for (int k = 0; k < 2; ++k) dst[m][k] = *(const PG8_LAS bf16x8*)(lds + PG8_SA(b, h) + aoff + m * 2048 + k * 1024); } while (0)
; #define PG8_LDB(dst, b, h) do { _Pragma("unroll") for (int n = 0; n < 2; ++n) _Pragma("unroll") for (int k = 0; k < 2; ++k) dst[n][k] = *(const PG8_LAS bf16x8*)(lds + PG8_SB(b, h) + boff + n * 2048 + k * 1024); } while (0)
; #define PG8_MMA(ai, bj, At, Bt) do { __builtin_amdgcn_s_setprio(1); _Pragma("unroll") for (int m = 0; m < 4; ++m) _Pragma("unroll") for (int n = 0; n < 2; ++n) _Pragma("unroll") for (int k = 0; k < 2; ++k) \
;         acc[ai][bj][m][n] = __builtin_amdgcn_mfma_f32_16x16x32_bf16(Bt[n][k], At[m][k], acc[ai][bj][m][n], 0, 0, 0); __builtin_amdgcn_s_setprio(0); } while (0)
; #define PG8_BAR __builtin_amdgcn_s_barrier()
; template <class Epi, class Sched, bool ALIGN_EPI = false, bool SP2 = false>
; __device__ __forceinline__ void gemm_phase(PG8_LAS unsigned char* lds, const Gemm g, const Sched& S, const Epi& E) {
;     ...
;         const bool has_next = S.next(ui + 1, nxt);
;         const char* nA = has_next ? (const char*)g.A + (size_t)nxt.pm * tstep : cA; const char* nB = has_next ? (const char*)g.Bt + (size_t)nxt.pn * tstep : cB;
;         for (int t = 0; t < nt; t += 2) {
;             const bool last = (t == nt - 2);
;             const char* a1 = cA + (size_t)(t + 1) * kstep;
;             const char* a2 = last ? nA : cA + (size_t)(t + 2) * kstep; const char* b2 = last ? nB : cB + (size_t)(t + 2) * kstep;
;             const char* a3 = a2 + kstep; const char* b3 = b2 + kstep;
;             if (last && has_next) S.a_ready(nxt);
;             if constexpr (SP2) {
;             PG8_LDB(B0, 0, 0); PG8_LDB(B1, 0, 1); PG8_SCHED; PG8_LDA(At, 0, 0); PG8_STAGE(PG8_SA(1, 1), a1 + hstep, voffA);
;             PG8_WAIT_V(8); PG8_WAIT_L(0); PG8_BAR; PG8_MMA(0, 0, At, B0); PG8_MMA(0, 1, At, B1); PG8_BAR; PG8_SCHED;
;             PG8_LDA(At, 0, 1); PG8_STAGE(PG8_SB(0, 0), b2, voffB); PG8_STAGE(PG8_SB(0, 1), b2 + hstep, voffB); PG8_STAGE(PG8_SA(0, 0), a2, voffA);
.LBB0_549:
	s_add_u32 s36, vcc_lo, 0xfffc0080
	s_addc_u32 s37, vcc_hi, -1
	s_add_i32 s66, 0, 0x10000
	s_cmp_eq_u32 s91, 12
	s_cselect_b32 s51, s35, s37
	s_cselect_b32 s50, s62, s36
	v_add_u32_e32 v148, s66, v150
	s_cselect_b32 s37, s43, s65
	s_cselect_b32 s36, s63, s64
	s_add_i32 s68, 0, 0x14000
	ds_read_b128 v[144:147], v148
	ds_read_b128 v[162:165], v148 offset:1024
	ds_read_b128 v[166:169], v148 offset:2048
	ds_read_b128 v[170:173], v148 offset:3072
	v_add_u32_e32 v148, s68, v150
	ds_read_b128 v[174:177], v148
	ds_read_b128 v[178:181], v148 offset:1024
	ds_read_b128 v[182:185], v148 offset:2048
	ds_read_b128 v[186:189], v148 offset:3072
	v_lshl_add_u64 v[148:149], vcc, 0, v[140:141]
	s_add_i32 m0, s4, 0xc000
	ds_read_b128 v[190:193], v161
	ds_read_b128 v[204:207], v161 offset:1024
	ds_read_b128 v[208:211], v161 offset:2048
	ds_read_b128 v[212:215], v161 offset:3072
	ds_read_b128 v[216:219], v161 offset:4096
	ds_read_b128 v[220:223], v161 offset:5120
	ds_read_b128 v[224:227], v161 offset:6144
	ds_read_b128 v[238:241], v161 offset:7168
	global_load_lds_dwordx4 v[148:149], off
	v_lshl_add_u64 v[148:149], vcc, 0, v[142:143]
	s_add_i32 m0, s4, 0xe000
	s_nop 0
	global_load_lds_dwordx4 v[148:149], off
	s_waitcnt vmcnt(8)
	s_waitcnt lgkmcnt(0)
	s_barrier
	s_setprio 1
	s_waitcnt lgkmcnt(0)
	v_mfma_f32_16x16x32_bf16 v[126:129], v[144:147], v[190:193], v[126:129]
	v_mfma_f32_16x16x32_bf16 v[118:121], v[166:169], v[190:193], v[118:121]
	v_mfma_f32_16x16x32_bf16 v[110:113], v[144:147], v[208:211], v[110:113]
	v_mfma_f32_16x16x32_bf16 v[102:105], v[166:169], v[208:211], v[102:105]
	v_mfma_f32_16x16x32_bf16 v[94:97], v[144:147], v[216:219], v[94:97]
	v_mfma_f32_16x16x32_bf16 v[86:89], v[166:169], v[216:219], v[86:89]
	v_mfma_f32_16x16x32_bf16 v[78:81], v[144:147], v[224:227], v[78:81]
	v_mfma_f32_16x16x32_bf16 v[70:73], v[166:169], v[224:227], v[70:73]
	v_mfma_f32_16x16x32_bf16 v[126:129], v[162:165], v[204:207], v[126:129]
	v_mfma_f32_16x16x32_bf16 v[118:121], v[170:173], v[204:207], v[118:121]
	v_mfma_f32_16x16x32_bf16 v[110:113], v[162:165], v[212:215], v[110:113]
	v_mfma_f32_16x16x32_bf16 v[102:105], v[170:173], v[212:215], v[102:105]
	v_mfma_f32_16x16x32_bf16 v[94:97], v[162:165], v[220:223], v[94:97]
	v_mfma_f32_16x16x32_bf16 v[86:89], v[170:173], v[220:223], v[86:89]
	v_mfma_f32_16x16x32_bf16 v[78:81], v[162:165], v[238:241], v[78:81]
	v_mfma_f32_16x16x32_bf16 v[70:73], v[170:173], v[238:241], v[70:73]
	v_mfma_f32_16x16x32_bf16 v[122:125], v[174:177], v[190:193], v[122:125]
	v_mfma_f32_16x16x32_bf16 v[114:117], v[182:185], v[190:193], v[114:117]
	v_mfma_f32_16x16x32_bf16 v[106:109], v[174:177], v[208:211], v[106:109]
	v_mfma_f32_16x16x32_bf16 v[98:101], v[182:185], v[208:211], v[98:101]
	v_mfma_f32_16x16x32_bf16 v[90:93], v[174:177], v[216:219], v[90:93]
	v_mfma_f32_16x16x32_bf16 v[82:85], v[182:185], v[216:219], v[82:85]
	v_mfma_f32_16x16x32_bf16 v[74:77], v[174:177], v[224:227], v[74:77]
	v_mfma_f32_16x16x32_bf16 v[66:69], v[182:185], v[224:227], v[66:69]
	v_mfma_f32_16x16x32_bf16 v[122:125], v[178:181], v[204:207], v[122:125]
	v_mfma_f32_16x16x32_bf16 v[114:117], v[186:189], v[204:207], v[114:117]
	v_mfma_f32_16x16x32_bf16 v[106:109], v[178:181], v[212:215], v[106:109]
	v_mfma_f32_16x16x32_bf16 v[98:101], v[186:189], v[212:215], v[98:101]
	v_mfma_f32_16x16x32_bf16 v[90:93], v[178:181], v[220:223], v[90:93]
	v_mfma_f32_16x16x32_bf16 v[82:85], v[186:189], v[220:223], v[82:85]
	v_mfma_f32_16x16x32_bf16 v[74:77], v[178:181], v[238:241], v[74:77]
	v_mfma_f32_16x16x32_bf16 v[66:69], v[186:189], v[238:241], v[66:69]
	s_setprio 0
	s_barrier
	s_add_i32 s66, s66, s56
	v_lshl_add_u64 v[148:149], s[36:37], 0, v[134:135]
	s_mov_b32 m0, s66
	ds_read_b128 v[190:193], v161 offset:16384
	ds_read_b128 v[204:207], v161 offset:17408
	ds_read_b128 v[208:211], v161 offset:18432
	ds_read_b128 v[212:215], v161 offset:19456
	ds_read_b128 v[216:219], v161 offset:20480
	ds_read_b128 v[220:223], v161 offset:21504
	ds_read_b128 v[224:227], v161 offset:22528
	ds_read_b128 v[238:241], v161 offset:23552
	global_load_lds_dwordx4 v[148:149], off
	s_add_i32 m0, s66, 0x2000
	s_add_u32 s66, s36, 0x40000
	v_lshl_add_u64 v[242:243], s[36:37], 0, v[130:131]
	s_addc_u32 s67, s37, 0
	s_add_i32 s68, s68, s56
	global_load_lds_dwordx4 v[242:243], off
	v_lshl_add_u64 v[244:245], s[66:67], 0, v[134:135]
	s_mov_b32 m0, s68
	v_lshl_add_u64 v[246:247], s[50:51], 0, v[132:133]
	global_load_lds_dwordx4 v[244:245], off
	v_lshl_add_u64 v[244:245], s[66:67], 0, v[130:131]
	s_add_i32 m0, s68, 0x2000
	s_nop 0
	global_load_lds_dwordx4 v[244:245], off
	v_lshl_add_u64 v[244:245], s[50:51], 0, v[136:137]
	s_mov_b32 m0, s4
	s_nop 0
	global_load_lds_dwordx4 v[244:245], off
	s_mov_b32 m0, s5
	s_nop 0
	global_load_lds_dwordx4 v[246:247], off
	s_waitcnt vmcnt(8)
	s_waitcnt lgkmcnt(0)
	s_barrier
; #define PG8_STAGE(bufoff, gbase, voff) do { _Pragma("unroll") for (int _i = 0; _i < 2; ++_i) \
;         __builtin_amdgcn_global_load_lds((const unsigned*)((const char*)(gbase) + (voff)[_i]), (PG8_LAS unsigned*)(lds + (bufoff) + ldsw + _i * 8192), 16, 0, 0); } while (0)
; #define PG8_LDA(dst, b, h) do { _Pragma("unroll") for (int m = 0; m < 4; ++m) _Pragma("unroll") for (int k = 0; k < 2; ++k) dst[m][k] = *(const PG8_LAS bf16x8*)(lds + PG8_SA(b, h) + aoff + m * 2048 + k * 1024); } while (0)
; #define PG8_LDB(dst, b, h) do { _Pragma("unroll") for (int n = 0; n < 2; ++n) _Pragma("unroll") for (int k = 0; k < 2; ++k) dst[n][k] = *(const PG8_LAS bf16x8*)(lds + PG8_SB(b, h) + boff + n * 2048 + k * 1024); } while (0)
; #define PG8_MMA(ai, bj, At, Bt) do { __builtin_amdgcn_s_setprio(1); _Pragma("unroll") for (int m = 0; m < 4; ++m) _Pragma("unroll") for (int n = 0; n < 2; ++n) _Pragma("unroll") for (int k = 0; k < 2; ++k) \
;         acc[ai][bj][m][n] = __builtin_amdgcn_mfma_f32_16x16x32_bf16(Bt[n][k], At[m][k], acc[ai][bj][m][n], 0, 0, 0); __builtin_amdgcn_s_setprio(0); } while (0)
; #define PG8_WAIT_V(n) asm volatile("s_waitcnt vmcnt(" #n ")" ::: "memory")
; #define PG8_WAIT_L(n) asm volatile("s_waitcnt lgkmcnt(" #n ")" ::: "memory")
; #define PG8_BAR __builtin_amdgcn_s_barrier()
; #define PG8_SCHED __builtin_amdgcn_sched_barrier(0)
; template <class Epi, class Sched, bool ALIGN_EPI = false, bool SP2 = false>
; __device__ __forceinline__ void gemm_phase(PG8_LAS unsigned char* lds, const Gemm g, const Sched& S, const Epi& E) {
;     ...
;             PG8_WAIT_V(8); PG8_WAIT_L(0); PG8_BAR; PG8_MMA(1, 0, At, B0); PG8_MMA(1, 1, At, B1); PG8_BAR; PG8_SCHED;
;             PG8_LDB(B0, 1, 0); PG8_LDB(B1, 1, 1); PG8_SCHED; PG8_LDA(At, 1, 0); PG8_STAGE(PG8_SA(0, 1), a2 + hstep, voffA);
;             PG8_WAIT_V(8); PG8_WAIT_L(0); PG8_BAR; PG8_MMA(0, 0, At, B0); PG8_MMA(0, 1, At, B1); PG8_BAR; PG8_SCHED;
	s_setprio 1
	s_waitcnt lgkmcnt(0)
	v_mfma_f32_16x16x32_bf16 v[62:65], v[144:147], v[190:193], v[62:65]
	v_mfma_f32_16x16x32_bf16 v[54:57], v[166:169], v[190:193], v[54:57]
	v_mfma_f32_16x16x32_bf16 v[46:49], v[144:147], v[208:211], v[46:49]
	v_mfma_f32_16x16x32_bf16 v[38:41], v[166:169], v[208:211], v[38:41]
	v_mfma_f32_16x16x32_bf16 v[28:31], v[144:147], v[216:219], v[28:31]
	v_mfma_f32_16x16x32_bf16 v[20:23], v[166:169], v[216:219], v[20:23]
	v_mfma_f32_16x16x32_bf16 v[12:15], v[144:147], v[224:227], v[12:15]
	v_mfma_f32_16x16x32_bf16 v[4:7], v[166:169], v[224:227], v[4:7]
	v_mfma_f32_16x16x32_bf16 v[62:65], v[162:165], v[204:207], v[62:65]
	v_mfma_f32_16x16x32_bf16 v[54:57], v[170:173], v[204:207], v[54:57]
	v_mfma_f32_16x16x32_bf16 v[46:49], v[162:165], v[212:215], v[46:49]
	v_mfma_f32_16x16x32_bf16 v[38:41], v[170:173], v[212:215], v[38:41]
	v_mfma_f32_16x16x32_bf16 v[28:31], v[162:165], v[220:223], v[28:31]
	v_mfma_f32_16x16x32_bf16 v[20:23], v[170:173], v[220:223], v[20:23]
	v_mfma_f32_16x16x32_bf16 v[12:15], v[162:165], v[238:241], v[12:15]
	v_mfma_f32_16x16x32_bf16 v[4:7], v[170:173], v[238:241], v[4:7]
	v_mfma_f32_16x16x32_bf16 v[58:61], v[174:177], v[190:193], v[58:61]
	v_mfma_f32_16x16x32_bf16 v[50:53], v[182:185], v[190:193], v[50:53]
	v_mfma_f32_16x16x32_bf16 v[42:45], v[174:177], v[208:211], v[42:45]
	v_mfma_f32_16x16x32_bf16 v[34:37], v[182:185], v[208:211], v[34:37]
	v_mfma_f32_16x16x32_bf16 v[24:27], v[174:177], v[216:219], v[24:27]
	v_mfma_f32_16x16x32_bf16 v[16:19], v[182:185], v[216:219], v[16:19]
	v_mfma_f32_16x16x32_bf16 v[8:11], v[174:177], v[224:227], v[8:11]
	v_mfma_f32_16x16x32_bf16 v[0:3], v[182:185], v[224:227], v[0:3]
	v_mfma_f32_16x16x32_bf16 v[58:61], v[178:181], v[204:207], v[58:61]
	v_mfma_f32_16x16x32_bf16 v[50:53], v[186:189], v[204:207], v[50:53]
	v_mfma_f32_16x16x32_bf16 v[42:45], v[178:181], v[212:215], v[42:45]
	v_mfma_f32_16x16x32_bf16 v[34:37], v[186:189], v[212:215], v[34:37]
	v_mfma_f32_16x16x32_bf16 v[24:27], v[178:181], v[220:223], v[24:27]
	v_mfma_f32_16x16x32_bf16 v[16:19], v[186:189], v[220:223], v[16:19]
	v_mfma_f32_16x16x32_bf16 v[8:11], v[178:181], v[238:241], v[8:11]
	v_mfma_f32_16x16x32_bf16 v[0:3], v[186:189], v[238:241], v[0:3]
	s_setprio 0
	s_barrier
	s_add_i32 s66, 0, 0x18000
	s_add_i32 s67, 0, 0x1c000
	v_add_u32_e32 v170, s66, v150
	v_add_u32_e32 v186, s67, v150
	ds_read_b128 v[144:147], v170
	ds_read_b128 v[162:165], v170 offset:1024
	ds_read_b128 v[166:169], v170 offset:2048
	ds_read_b128 v[170:173], v170 offset:3072
	ds_read_b128 v[174:177], v186
	ds_read_b128 v[178:181], v186 offset:1024
	ds_read_b128 v[182:185], v186 offset:2048
	ds_read_b128 v[186:189], v186 offset:3072
	s_add_u32 s50, s50, 0x40000
	s_addc_u32 s51, s51, 0
	s_mov_b32 m0, s52
	v_lshl_add_u64 v[248:249], s[50:51], 0, v[136:137]
	ds_read_b128 v[190:193], v161 offset:32768
	ds_read_b128 v[204:207], v161 offset:33792
	ds_read_b128 v[208:211], v161 offset:34816
	ds_read_b128 v[212:215], v161 offset:35840
	ds_read_b128 v[216:219], v161 offset:36864
	ds_read_b128 v[220:223], v161 offset:37888
	ds_read_b128 v[224:227], v161 offset:38912
	ds_read_b128 v[238:241], v161 offset:39936
	global_load_lds_dwordx4 v[248:249], off
	v_lshl_add_u64 v[248:249], s[50:51], 0, v[132:133]
	s_mov_b32 m0, s53
	s_nop 0
	global_load_lds_dwordx4 v[248:249], off
	s_waitcnt vmcnt(8)
	s_waitcnt lgkmcnt(0)
	s_barrier
	s_setprio 1
	s_waitcnt lgkmcnt(0)
	v_mfma_f32_16x16x32_bf16 v[126:129], v[144:147], v[190:193], v[126:129]
	v_mfma_f32_16x16x32_bf16 v[118:121], v[166:169], v[190:193], v[118:121]
	v_mfma_f32_16x16x32_bf16 v[110:113], v[144:147], v[208:211], v[110:113]
	v_mfma_f32_16x16x32_bf16 v[102:105], v[166:169], v[208:211], v[102:105]
	v_mfma_f32_16x16x32_bf16 v[94:97], v[144:147], v[216:219], v[94:97]
	v_mfma_f32_16x16x32_bf16 v[86:89], v[166:169], v[216:219], v[86:89]
	v_mfma_f32_16x16x32_bf16 v[78:81], v[144:147], v[224:227], v[78:81]
	v_mfma_f32_16x16x32_bf16 v[70:73], v[166:169], v[224:227], v[70:73]
	v_mfma_f32_16x16x32_bf16 v[126:129], v[162:165], v[204:207], v[126:129]
	v_mfma_f32_16x16x32_bf16 v[118:121], v[170:173], v[204:207], v[118:121]
	v_mfma_f32_16x16x32_bf16 v[110:113], v[162:165], v[212:215], v[110:113]
	v_mfma_f32_16x16x32_bf16 v[102:105], v[170:173], v[212:215], v[102:105]
	v_mfma_f32_16x16x32_bf16 v[94:97], v[162:165], v[220:223], v[94:97]
	v_mfma_f32_16x16x32_bf16 v[86:89], v[170:173], v[220:223], v[86:89]
	v_mfma_f32_16x16x32_bf16 v[78:81], v[162:165], v[238:241], v[78:81]
	v_mfma_f32_16x16x32_bf16 v[70:73], v[170:173], v[238:241], v[70:73]
	v_mfma_f32_16x16x32_bf16 v[122:125], v[174:177], v[190:193], v[122:125]
	v_mfma_f32_16x16x32_bf16 v[114:117], v[182:185], v[190:193], v[114:117]
	v_mfma_f32_16x16x32_bf16 v[106:109], v[174:177], v[208:211], v[106:109]
	v_mfma_f32_16x16x32_bf16 v[98:101], v[182:185], v[208:211], v[98:101]
	v_mfma_f32_16x16x32_bf16 v[90:93], v[174:177], v[216:219], v[90:93]
	v_mfma_f32_16x16x32_bf16 v[82:85], v[182:185], v[216:219], v[82:85]
	v_mfma_f32_16x16x32_bf16 v[74:77], v[174:177], v[224:227], v[74:77]
	v_mfma_f32_16x16x32_bf16 v[66:69], v[182:185], v[224:227], v[66:69]
	v_mfma_f32_16x16x32_bf16 v[122:125], v[178:181], v[204:207], v[122:125]
	v_mfma_f32_16x16x32_bf16 v[114:117], v[186:189], v[204:207], v[114:117]
	v_mfma_f32_16x16x32_bf16 v[106:109], v[178:181], v[212:215], v[106:109]
	v_mfma_f32_16x16x32_bf16 v[98:101], v[186:189], v[212:215], v[98:101]
	v_mfma_f32_16x16x32_bf16 v[90:93], v[178:181], v[220:223], v[90:93]
	v_mfma_f32_16x16x32_bf16 v[82:85], v[186:189], v[220:223], v[82:85]
	v_mfma_f32_16x16x32_bf16 v[74:77], v[178:181], v[238:241], v[74:77]
	v_mfma_f32_16x16x32_bf16 v[66:69], v[186:189], v[238:241], v[66:69]
	s_setprio 0
	s_barrier
; #define PG8_STAGE(bufoff, gbase, voff) do { _Pragma("unroll") for (int _i = 0; _i < 2; ++_i) \
;         __builtin_amdgcn_global_load_lds((const unsigned*)((const char*)(gbase) + (voff)[_i]), (PG8_LAS unsigned*)(lds + (bufoff) + ldsw + _i * 8192), 16, 0, 0); } while (0)
; #define PG8_LDA(dst, b, h) do { _Pragma("unroll") for (int m = 0; m < 4; ++m) _Pragma("unroll") for (int k = 0; k < 2; ++k) dst[m][k] = *(const PG8_LAS bf16x8*)(lds + PG8_SA(b, h) + aoff + m * 2048 + k * 1024); } while (0)
; #define PG8_MMA(ai, bj, At, Bt) do { __builtin_amdgcn_s_setprio(1); _Pragma("unroll") for (int m = 0; m < 4; ++m) _Pragma("unroll") for (int n = 0; n < 2; ++n) _Pragma("unroll") for (int k = 0; k < 2; ++k) \
;         acc[ai][bj][m][n] = __builtin_amdgcn_mfma_f32_16x16x32_bf16(Bt[n][k], At[m][k], acc[ai][bj][m][n], 0, 0, 0); __builtin_amdgcn_s_setprio(0); } while (0)
; #define PG8_WAIT_V(n) asm volatile("s_waitcnt vmcnt(" #n ")" ::: "memory")
; #define PG8_WAIT_L(n) asm volatile("s_waitcnt lgkmcnt(" #n ")" ::: "memory")
; #define PG8_BAR __builtin_amdgcn_s_barrier()
; #define PG8_SCHED __builtin_amdgcn_sched_barrier(0)
; template <class Epi, class Sched, bool ALIGN_EPI = false, bool SP2 = false>
; __device__ __forceinline__ void gemm_phase(PG8_LAS unsigned char* lds, const Gemm g, const Sched& S, const Epi& E) {
;     ...
;             PG8_LDA(At, 1, 1); PG8_STAGE(PG8_SB(1, 0), b3, voffB); PG8_STAGE(PG8_SB(1, 1), b3 + hstep, voffB); PG8_STAGE(PG8_SA(1, 0), a3, voffA);
;             PG8_WAIT_V(8); PG8_WAIT_L(0); PG8_BAR; PG8_MMA(1, 0, At, B0); PG8_MMA(1, 1, At, B1); PG8_BAR; PG8_SCHED;
	s_add_i32 s50, s66, s56
	v_lshl_add_u64 v[148:149], v[148:149], 0, s[8:9]
	s_mov_b32 m0, s50
	ds_read_b128 v[190:193], v161 offset:49152
	ds_read_b128 v[204:207], v161 offset:50176
	ds_read_b128 v[208:211], v161 offset:51200
	ds_read_b128 v[212:215], v161 offset:52224
	ds_read_b128 v[216:219], v161 offset:53248
	ds_read_b128 v[220:223], v161 offset:54272
	ds_read_b128 v[224:227], v161 offset:55296
	ds_read_b128 v[238:241], v161 offset:56320
	global_load_lds_dwordx4 v[148:149], off
	s_add_i32 m0, s50, 0x2000
	s_add_u32 s36, s36, 0x40080
	v_lshl_add_u64 v[148:149], v[242:243], 0, s[8:9]
	s_addc_u32 s37, s37, 0
	s_add_i32 s50, s67, s56
	global_load_lds_dwordx4 v[148:149], off
	v_lshl_add_u64 v[148:149], s[36:37], 0, v[134:135]
	s_mov_b32 m0, s50
	s_nop 0
	global_load_lds_dwordx4 v[148:149], off
	v_lshl_add_u64 v[148:149], s[36:37], 0, v[130:131]
	s_add_i32 m0, s50, 0x2000
	s_nop 0
	global_load_lds_dwordx4 v[148:149], off
	v_lshl_add_u64 v[148:149], v[244:245], 0, s[8:9]
	s_mov_b32 m0, s58
	s_nop 0
	global_load_lds_dwordx4 v[148:149], off
	v_lshl_add_u64 v[148:149], v[246:247], 0, s[8:9]
	s_mov_b32 m0, s59
	s_nop 0
	global_load_lds_dwordx4 v[148:149], off
	s_waitcnt vmcnt(8)
	s_waitcnt lgkmcnt(0)
	s_barrier
	s_setprio 1
	s_waitcnt lgkmcnt(0)
	v_mfma_f32_16x16x32_bf16 v[62:65], v[144:147], v[190:193], v[62:65]
	v_mfma_f32_16x16x32_bf16 v[54:57], v[166:169], v[190:193], v[54:57]
	v_mfma_f32_16x16x32_bf16 v[46:49], v[144:147], v[208:211], v[46:49]
	v_mfma_f32_16x16x32_bf16 v[38:41], v[166:169], v[208:211], v[38:41]
	v_mfma_f32_16x16x32_bf16 v[28:31], v[144:147], v[216:219], v[28:31]
	v_mfma_f32_16x16x32_bf16 v[20:23], v[166:169], v[216:219], v[20:23]
	v_mfma_f32_16x16x32_bf16 v[12:15], v[144:147], v[224:227], v[12:15]
	v_mfma_f32_16x16x32_bf16 v[4:7], v[166:169], v[224:227], v[4:7]
	v_mfma_f32_16x16x32_bf16 v[62:65], v[162:165], v[204:207], v[62:65]
	v_mfma_f32_16x16x32_bf16 v[54:57], v[170:173], v[204:207], v[54:57]
	v_mfma_f32_16x16x32_bf16 v[46:49], v[162:165], v[212:215], v[46:49]
	v_mfma_f32_16x16x32_bf16 v[38:41], v[170:173], v[212:215], v[38:41]
	v_mfma_f32_16x16x32_bf16 v[28:31], v[162:165], v[220:223], v[28:31]
	v_mfma_f32_16x16x32_bf16 v[20:23], v[170:173], v[220:223], v[20:23]
	v_mfma_f32_16x16x32_bf16 v[12:15], v[162:165], v[238:241], v[12:15]
	v_mfma_f32_16x16x32_bf16 v[4:7], v[170:173], v[238:241], v[4:7]
	v_mfma_f32_16x16x32_bf16 v[58:61], v[174:177], v[190:193], v[58:61]
	v_mfma_f32_16x16x32_bf16 v[50:53], v[182:185], v[190:193], v[50:53]
	v_mfma_f32_16x16x32_bf16 v[42:45], v[174:177], v[208:211], v[42:45]
	v_mfma_f32_16x16x32_bf16 v[34:37], v[182:185], v[208:211], v[34:37]
	v_mfma_f32_16x16x32_bf16 v[24:27], v[174:177], v[216:219], v[24:27]
	v_mfma_f32_16x16x32_bf16 v[16:19], v[182:185], v[216:219], v[16:19]
	v_mfma_f32_16x16x32_bf16 v[8:11], v[174:177], v[224:227], v[8:11]
	v_mfma_f32_16x16x32_bf16 v[0:3], v[182:185], v[224:227], v[0:3]
	v_mfma_f32_16x16x32_bf16 v[58:61], v[178:181], v[204:207], v[58:61]
	v_mfma_f32_16x16x32_bf16 v[50:53], v[186:189], v[204:207], v[50:53]
	v_mfma_f32_16x16x32_bf16 v[42:45], v[178:181], v[212:215], v[42:45]
	v_mfma_f32_16x16x32_bf16 v[34:37], v[186:189], v[212:215], v[34:37]
	v_mfma_f32_16x16x32_bf16 v[24:27], v[178:181], v[220:223], v[24:27]
	v_mfma_f32_16x16x32_bf16 v[16:19], v[186:189], v[220:223], v[16:19]
	v_mfma_f32_16x16x32_bf16 v[8:11], v[178:181], v[238:241], v[8:11]
	v_mfma_f32_16x16x32_bf16 v[0:3], v[186:189], v[238:241], v[0:3]
	s_setprio 0
	s_barrier
	s_add_i32 s91, s91, 2
	s_add_u32 vcc_lo, vcc_lo, 0x100
	s_addc_u32 vcc_hi, vcc_hi, 0
	s_add_u32 s64, s64, 0x100
	s_addc_u32 s65, s65, 0
	s_cmp_gt_u32 s91, 13
	s_cbranch_scc0 .LBB0_549
	s_and_b64 vcc, exec, s[30:31]
	s_cbranch_vccz .LBB0_552
	s_barrier

; #define PG8_STAGE(bufoff, gbase, voff) do { _Pragma("unroll") for (int _i = 0; _i < 2; ++_i) \
;         __builtin_amdgcn_global_load_lds((const unsigned*)((const char*)(gbase) + (voff)[_i]), (PG8_LAS unsigned*)(lds + (bufoff) + ldsw + _i * 8192), 16, 0, 0); } while (0)
; #define PG8_LDA(dst, b, h) do { _Pragma("unroll") for (int m = 0; m < 4; ++m) _Pragma("unroll") for (int k = 0; k < 2; ++k) dst[m][k] = *(const PG8_LAS bf16x8*)(lds + PG8_SA(b, h) + aoff + m * 2048 + k * 1024); } while (0)
; #define PG8_LDB(dst, b, h) do { _Pragma("unroll") for (int n = 0; n < 2; ++n) _Pragma("unroll") for (int k = 0; k < 2; ++k) dst[n][k] = *(const PG8_LAS bf16x8*)(lds + PG8_SB(b, h) + boff + n * 2048 + k * 1024); } while (0)
; #define PG8_MMA(ai, bj, At, Bt) do { __builtin_amdgcn_s_setprio(1); _Pragma("unroll") for (int m = 0; m < 4; ++m) _Pragma("unroll") for (int n = 0; n < 2; ++n) _Pragma("unroll") for (int k = 0; k < 2; ++k) \
;         acc[ai][bj][m][n] = __builtin_amdgcn_mfma_f32_16x16x32_bf16(Bt[n][k], At[m][k], acc[ai][bj][m][n], 0, 0, 0); __builtin_amdgcn_s_setprio(0); } while (0)
; #define PG8_BAR __builtin_amdgcn_s_barrier()
; template <class Epi, class Sched, bool ALIGN_EPI = false, bool SP2 = false>
; __device__ __forceinline__ void gemm_phase(PG8_LAS unsigned char* lds, const Gemm g, const Sched& S, const Epi& E) {
;     ...
;         const bool has_next = S.next(ui + 1, nxt);
;         const char* nA = has_next ? (const char*)g.A + (size_t)nxt.pm * tstep : cA; const char* nB = has_next ? (const char*)g.Bt + (size_t)nxt.pn * tstep : cB;
;         for (int t = 0; t < nt; t += 2) {
;             const bool last = (t == nt - 2);
;             const char* a1 = cA + (size_t)(t + 1) * kstep;
;             const char* a2 = last ? nA : cA + (size_t)(t + 2) * kstep; const char* b2 = last ? nB : cB + (size_t)(t + 2) * kstep;
;             const char* a3 = a2 + kstep; const char* b3 = b2 + kstep;
;             if (last && has_next) S.a_ready(nxt);
;             if constexpr (SP2) {
;             PG8_LDB(B0, 0, 0); PG8_LDB(B1, 0, 1); PG8_SCHED; PG8_LDA(At, 0, 0); PG8_STAGE(PG8_SA(1, 1), a1 + hstep, voffA);
;             PG8_WAIT_V(8); PG8_WAIT_L(0); PG8_BAR; PG8_MMA(0, 0, At, B0); PG8_MMA(0, 1, At, B1); PG8_BAR; PG8_SCHED;
;             PG8_LDA(At, 0, 1); PG8_STAGE(PG8_SB(0, 0), b2, voffB); PG8_STAGE(PG8_SB(0, 1), b2 + hstep, voffB); PG8_STAGE(PG8_SA(0, 0), a2, voffA);
.LBB0_826:
	s_add_i32 s68, s46, 2
	s_add_u32 s69, s30, vcc_lo
	s_addc_u32 s47, s31, vcc_hi
	s_add_u32 s70, s6, vcc_lo
	s_addc_u32 s71, s7, vcc_hi
	s_add_i32 s72, 0, 0x10000
	s_cmp_eq_u32 s63, s46
	s_cselect_b32 s47, s37, s47
	s_cselect_b32 s46, s66, s69
	v_add_u32_e32 v33, s72, v106
	s_cselect_b32 s71, s35, s71
	s_cselect_b32 s70, s67, s70
	s_add_i32 s69, 0, 0x14000
	ds_read_b128 v[116:119], v33
	ds_read_b128 v[148:151], v33 offset:1024
	ds_read_b128 v[152:155], v33 offset:2048
	ds_read_b128 v[156:159], v33 offset:3072
	v_add_u32_e32 v33, s69, v106
	ds_read_b128 v[160:163], v33
	ds_read_b128 v[164:167], v33 offset:1024
	ds_read_b128 v[168:171], v33 offset:2048
	ds_read_b128 v[172:175], v33 offset:3072
	v_lshl_add_u64 v[220:221], s[30:31], 0, v[104:105]
	s_add_i32 m0, s19, 0xc000
	ds_read_b128 v[176:179], v107
	ds_read_b128 v[180:183], v107 offset:1024
	ds_read_b128 v[184:187], v107 offset:2048
	ds_read_b128 v[188:191], v107 offset:3072
	ds_read_b128 v[204:207], v107 offset:4096
	ds_read_b128 v[208:211], v107 offset:5120
	ds_read_b128 v[212:215], v107 offset:6144
	ds_read_b128 v[216:219], v107 offset:7168
	global_load_lds_dwordx4 v[220:221], off
	v_lshl_add_u64 v[220:221], s[30:31], 0, v[34:35]
	s_add_i32 m0, s19, 0xe000
	s_nop 0
	global_load_lds_dwordx4 v[220:221], off
	s_waitcnt vmcnt(8)
	s_waitcnt lgkmcnt(0)
	s_barrier
	s_setprio 1
	s_waitcnt lgkmcnt(0)
	v_mfma_f32_16x16x32_bf16 v[144:147], v[116:119], v[176:179], v[144:147]
	v_mfma_f32_16x16x32_bf16 v[140:143], v[152:155], v[176:179], v[140:143]
	v_mfma_f32_16x16x32_bf16 v[128:131], v[116:119], v[184:187], v[128:131]
	v_mfma_f32_16x16x32_bf16 v[124:127], v[152:155], v[184:187], v[124:127]
	v_mfma_f32_16x16x32_bf16 v[108:111], v[116:119], v[204:207], v[108:111]
	v_mfma_f32_16x16x32_bf16 v[96:99], v[152:155], v[204:207], v[96:99]
	v_mfma_f32_16x16x32_bf16 v[80:83], v[116:119], v[212:215], v[80:83]
	v_mfma_f32_16x16x32_bf16 v[76:79], v[152:155], v[212:215], v[76:79]
	v_mfma_f32_16x16x32_bf16 v[144:147], v[148:151], v[180:183], v[144:147]
	v_mfma_f32_16x16x32_bf16 v[140:143], v[156:159], v[180:183], v[140:143]
	v_mfma_f32_16x16x32_bf16 v[128:131], v[148:151], v[188:191], v[128:131]
	v_mfma_f32_16x16x32_bf16 v[124:127], v[156:159], v[188:191], v[124:127]
	v_mfma_f32_16x16x32_bf16 v[108:111], v[148:151], v[208:211], v[108:111]
	v_mfma_f32_16x16x32_bf16 v[96:99], v[156:159], v[208:211], v[96:99]
	v_mfma_f32_16x16x32_bf16 v[80:83], v[148:151], v[216:219], v[80:83]
	v_mfma_f32_16x16x32_bf16 v[76:79], v[156:159], v[216:219], v[76:79]
	v_mfma_f32_16x16x32_bf16 v[136:139], v[160:163], v[176:179], v[136:139]
	v_mfma_f32_16x16x32_bf16 v[132:135], v[168:171], v[176:179], v[132:135]
	v_mfma_f32_16x16x32_bf16 v[120:123], v[160:163], v[184:187], v[120:123]
	v_mfma_f32_16x16x32_bf16 v[112:115], v[168:171], v[184:187], v[112:115]
	v_mfma_f32_16x16x32_bf16 v[88:91], v[160:163], v[204:207], v[88:91]
	v_mfma_f32_16x16x32_bf16 v[84:87], v[168:171], v[204:207], v[84:87]
	v_mfma_f32_16x16x32_bf16 v[72:75], v[160:163], v[212:215], v[72:75]
	v_mfma_f32_16x16x32_bf16 v[68:71], v[168:171], v[212:215], v[68:71]
	v_mfma_f32_16x16x32_bf16 v[136:139], v[164:167], v[180:183], v[136:139]
	v_mfma_f32_16x16x32_bf16 v[132:135], v[172:175], v[180:183], v[132:135]
	v_mfma_f32_16x16x32_bf16 v[120:123], v[164:167], v[188:191], v[120:123]
	v_mfma_f32_16x16x32_bf16 v[112:115], v[172:175], v[188:191], v[112:115]
	v_mfma_f32_16x16x32_bf16 v[88:91], v[164:167], v[208:211], v[88:91]
	v_mfma_f32_16x16x32_bf16 v[84:87], v[172:175], v[208:211], v[84:87]
	v_mfma_f32_16x16x32_bf16 v[72:75], v[164:167], v[216:219], v[72:75]
	v_mfma_f32_16x16x32_bf16 v[68:71], v[172:175], v[216:219], v[68:71]
	s_setprio 0
	s_barrier
	s_add_i32 s72, s72, s45
	v_lshl_add_u64 v[220:221], s[70:71], 0, v[92:93]
	s_mov_b32 m0, s72
	ds_read_b128 v[176:179], v107 offset:16384
	ds_read_b128 v[180:183], v107 offset:17408
	ds_read_b128 v[184:187], v107 offset:18432
	ds_read_b128 v[188:191], v107 offset:19456
	ds_read_b128 v[204:207], v107 offset:20480
	ds_read_b128 v[208:211], v107 offset:21504
	ds_read_b128 v[212:215], v107 offset:22528
	ds_read_b128 v[216:219], v107 offset:23552
	global_load_lds_dwordx4 v[220:221], off
	s_add_i32 m0, s72, 0x2000
	v_lshl_add_u64 v[222:223], s[70:71], 0, v[94:95]
	s_add_u32 s70, s70, s17
	s_addc_u32 s71, s71, 0
	s_add_i32 s69, s69, s45
	global_load_lds_dwordx4 v[222:223], off
	v_lshl_add_u64 v[224:225], s[70:71], 0, v[92:93]
	s_mov_b32 m0, s69
	v_lshl_add_u64 v[226:227], s[70:71], 0, v[94:95]
	global_load_lds_dwordx4 v[224:225], off
	s_add_i32 m0, s69, 0x2000
	v_lshl_add_u64 v[238:239], s[46:47], 0, v[92:93]
	global_load_lds_dwordx4 v[226:227], off
	s_mov_b32 m0, s19
	v_lshl_add_u64 v[240:241], s[46:47], 0, v[94:95]
	global_load_lds_dwordx4 v[238:239], off
	s_mov_b32 m0, s57
	s_nop 0
	global_load_lds_dwordx4 v[240:241], off
	s_waitcnt vmcnt(8)
	s_waitcnt lgkmcnt(0)
	s_barrier
; #define PG8_STAGE(bufoff, gbase, voff) do { _Pragma("unroll") for (int _i = 0; _i < 2; ++_i) \
;         __builtin_amdgcn_global_load_lds((const unsigned*)((const char*)(gbase) + (voff)[_i]), (PG8_LAS unsigned*)(lds + (bufoff) + ldsw + _i * 8192), 16, 0, 0); } while (0)
; #define PG8_LDA(dst, b, h) do { _Pragma("unroll") for (int m = 0; m < 4; ++m) _Pragma("unroll") for (int k = 0; k < 2; ++k) dst[m][k] = *(const PG8_LAS bf16x8*)(lds + PG8_SA(b, h) + aoff + m * 2048 + k * 1024); } while (0)
; #define PG8_LDB(dst, b, h) do { _Pragma("unroll") for (int n = 0; n < 2; ++n) _Pragma("unroll") for (int k = 0; k < 2; ++k) dst[n][k] = *(const PG8_LAS bf16x8*)(lds + PG8_SB(b, h) + boff + n * 2048 + k * 1024); } while (0)
; #define PG8_MMA(ai, bj, At, Bt) do { __builtin_amdgcn_s_setprio(1); _Pragma("unroll") for (int m = 0; m < 4; ++m) _Pragma("unroll") for (int n = 0; n < 2; ++n) _Pragma("unroll") for (int k = 0; k < 2; ++k) \
;         acc[ai][bj][m][n] = __builtin_amdgcn_mfma_f32_16x16x32_bf16(Bt[n][k], At[m][k], acc[ai][bj][m][n], 0, 0, 0); __builtin_amdgcn_s_setprio(0); } while (0)
; #define PG8_WAIT_V(n) asm volatile("s_waitcnt vmcnt(" #n ")" ::: "memory")
; #define PG8_WAIT_L(n) asm volatile("s_waitcnt lgkmcnt(" #n ")" ::: "memory")
; #define PG8_BAR __builtin_amdgcn_s_barrier()
; #define PG8_SCHED __builtin_amdgcn_sched_barrier(0)
; template <class Epi, class Sched, bool ALIGN_EPI = false, bool SP2 = false>
; __device__ __forceinline__ void gemm_phase(PG8_LAS unsigned char* lds, const Gemm g, const Sched& S, const Epi& E) {
;     ...
;             PG8_WAIT_V(8); PG8_WAIT_L(0); PG8_BAR; PG8_MMA(1, 0, At, B0); PG8_MMA(1, 1, At, B1); PG8_BAR; PG8_SCHED;
;             PG8_LDB(B0, 1, 0); PG8_LDB(B1, 1, 1); PG8_SCHED; PG8_LDA(At, 1, 0); PG8_STAGE(PG8_SA(0, 1), a2 + hstep, voffA);
;             PG8_WAIT_V(8); PG8_WAIT_L(0); PG8_BAR; PG8_MMA(0, 0, At, B0); PG8_MMA(0, 1, At, B1); PG8_BAR; PG8_SCHED;
	s_setprio 1
	s_waitcnt lgkmcnt(0)
	v_mfma_f32_16x16x32_bf16 v[64:67], v[116:119], v[176:179], v[64:67]
	v_mfma_f32_16x16x32_bf16 v[60:63], v[152:155], v[176:179], v[60:63]
	v_mfma_f32_16x16x32_bf16 v[48:51], v[116:119], v[184:187], v[48:51]
	v_mfma_f32_16x16x32_bf16 v[44:47], v[152:155], v[184:187], v[44:47]
	v_mfma_f32_16x16x32_bf16 v[28:31], v[116:119], v[204:207], v[28:31]
	v_mfma_f32_16x16x32_bf16 v[24:27], v[152:155], v[204:207], v[24:27]
	v_mfma_f32_16x16x32_bf16 v[12:15], v[116:119], v[212:215], v[12:15]
	v_mfma_f32_16x16x32_bf16 v[8:11], v[152:155], v[212:215], v[8:11]
	v_mfma_f32_16x16x32_bf16 v[64:67], v[148:151], v[180:183], v[64:67]
	v_mfma_f32_16x16x32_bf16 v[60:63], v[156:159], v[180:183], v[60:63]
	v_mfma_f32_16x16x32_bf16 v[48:51], v[148:151], v[188:191], v[48:51]
	v_mfma_f32_16x16x32_bf16 v[44:47], v[156:159], v[188:191], v[44:47]
	v_mfma_f32_16x16x32_bf16 v[28:31], v[148:151], v[208:211], v[28:31]
	v_mfma_f32_16x16x32_bf16 v[24:27], v[156:159], v[208:211], v[24:27]
	v_mfma_f32_16x16x32_bf16 v[12:15], v[148:151], v[216:219], v[12:15]
	v_mfma_f32_16x16x32_bf16 v[8:11], v[156:159], v[216:219], v[8:11]
	v_mfma_f32_16x16x32_bf16 v[56:59], v[160:163], v[176:179], v[56:59]
	v_mfma_f32_16x16x32_bf16 v[52:55], v[168:171], v[176:179], v[52:55]
	v_mfma_f32_16x16x32_bf16 v[40:43], v[160:163], v[184:187], v[40:43]
	v_mfma_f32_16x16x32_bf16 v[36:39], v[168:171], v[184:187], v[36:39]
	v_mfma_f32_16x16x32_bf16 v[20:23], v[160:163], v[204:207], v[20:23]
	v_mfma_f32_16x16x32_bf16 v[16:19], v[168:171], v[204:207], v[16:19]
	v_mfma_f32_16x16x32_bf16 v[4:7], v[160:163], v[212:215], v[4:7]
	v_mfma_f32_16x16x32_bf16 v[0:3], v[168:171], v[212:215], v[0:3]
	v_mfma_f32_16x16x32_bf16 v[56:59], v[164:167], v[180:183], v[56:59]
	v_mfma_f32_16x16x32_bf16 v[52:55], v[172:175], v[180:183], v[52:55]
	v_mfma_f32_16x16x32_bf16 v[40:43], v[164:167], v[188:191], v[40:43]
	v_mfma_f32_16x16x32_bf16 v[36:39], v[172:175], v[188:191], v[36:39]
	v_mfma_f32_16x16x32_bf16 v[20:23], v[164:167], v[208:211], v[20:23]
	v_mfma_f32_16x16x32_bf16 v[16:19], v[172:175], v[208:211], v[16:19]
	v_mfma_f32_16x16x32_bf16 v[4:7], v[164:167], v[216:219], v[4:7]
	v_mfma_f32_16x16x32_bf16 v[0:3], v[172:175], v[216:219], v[0:3]
	s_setprio 0
	s_barrier
	s_add_i32 s69, 0, 0x18000
	v_add_u32_e32 v33, s69, v106
	s_add_i32 s70, 0, 0x1c000
	ds_read_b128 v[116:119], v33
	ds_read_b128 v[148:151], v33 offset:1024
	ds_read_b128 v[152:155], v33 offset:2048
	ds_read_b128 v[156:159], v33 offset:3072
	v_add_u32_e32 v33, s70, v106
	ds_read_b128 v[160:163], v33
	ds_read_b128 v[164:167], v33 offset:1024
	ds_read_b128 v[168:171], v33 offset:2048
	ds_read_b128 v[172:175], v33 offset:3072
	s_add_u32 s46, s46, s17
	s_addc_u32 s47, s47, 0
	s_mov_b32 m0, s58
	v_lshl_add_u64 v[242:243], s[46:47], 0, v[92:93]
	ds_read_b128 v[176:179], v107 offset:32768
	ds_read_b128 v[180:183], v107 offset:33792
	ds_read_b128 v[184:187], v107 offset:34816
	ds_read_b128 v[188:191], v107 offset:35840
	ds_read_b128 v[204:207], v107 offset:36864
	ds_read_b128 v[208:211], v107 offset:37888
	ds_read_b128 v[212:215], v107 offset:38912
	ds_read_b128 v[216:219], v107 offset:39936
	global_load_lds_dwordx4 v[242:243], off
	v_lshl_add_u64 v[242:243], s[46:47], 0, v[94:95]
	s_mov_b32 m0, s59
	s_nop 0
	global_load_lds_dwordx4 v[242:243], off
	s_waitcnt vmcnt(8)
	s_waitcnt lgkmcnt(0)
	s_barrier
	s_setprio 1
	s_waitcnt lgkmcnt(0)
	v_mfma_f32_16x16x32_bf16 v[144:147], v[116:119], v[176:179], v[144:147]
	v_mfma_f32_16x16x32_bf16 v[140:143], v[152:155], v[176:179], v[140:143]
	v_mfma_f32_16x16x32_bf16 v[128:131], v[116:119], v[184:187], v[128:131]
	v_mfma_f32_16x16x32_bf16 v[124:127], v[152:155], v[184:187], v[124:127]
	v_mfma_f32_16x16x32_bf16 v[108:111], v[116:119], v[204:207], v[108:111]
	v_mfma_f32_16x16x32_bf16 v[96:99], v[152:155], v[204:207], v[96:99]
	v_mfma_f32_16x16x32_bf16 v[80:83], v[116:119], v[212:215], v[80:83]
	v_mfma_f32_16x16x32_bf16 v[76:79], v[152:155], v[212:215], v[76:79]
	v_mfma_f32_16x16x32_bf16 v[144:147], v[148:151], v[180:183], v[144:147]
	v_mfma_f32_16x16x32_bf16 v[140:143], v[156:159], v[180:183], v[140:143]
	v_mfma_f32_16x16x32_bf16 v[128:131], v[148:151], v[188:191], v[128:131]
	v_mfma_f32_16x16x32_bf16 v[124:127], v[156:159], v[188:191], v[124:127]
	v_mfma_f32_16x16x32_bf16 v[108:111], v[148:151], v[208:211], v[108:111]
	v_mfma_f32_16x16x32_bf16 v[96:99], v[156:159], v[208:211], v[96:99]
	v_mfma_f32_16x16x32_bf16 v[80:83], v[148:151], v[216:219], v[80:83]
	v_mfma_f32_16x16x32_bf16 v[76:79], v[156:159], v[216:219], v[76:79]
	v_mfma_f32_16x16x32_bf16 v[136:139], v[160:163], v[176:179], v[136:139]
	v_mfma_f32_16x16x32_bf16 v[132:135], v[168:171], v[176:179], v[132:135]
	v_mfma_f32_16x16x32_bf16 v[120:123], v[160:163], v[184:187], v[120:123]
	v_mfma_f32_16x16x32_bf16 v[112:115], v[168:171], v[184:187], v[112:115]
	v_mfma_f32_16x16x32_bf16 v[88:91], v[160:163], v[204:207], v[88:91]
	v_mfma_f32_16x16x32_bf16 v[84:87], v[168:171], v[204:207], v[84:87]
	v_mfma_f32_16x16x32_bf16 v[72:75], v[160:163], v[212:215], v[72:75]
	v_mfma_f32_16x16x32_bf16 v[68:71], v[168:171], v[212:215], v[68:71]
	v_mfma_f32_16x16x32_bf16 v[136:139], v[164:167], v[180:183], v[136:139]
	v_mfma_f32_16x16x32_bf16 v[132:135], v[172:175], v[180:183], v[132:135]
	v_mfma_f32_16x16x32_bf16 v[120:123], v[164:167], v[188:191], v[120:123]
	v_mfma_f32_16x16x32_bf16 v[112:115], v[172:175], v[188:191], v[112:115]
	v_mfma_f32_16x16x32_bf16 v[88:91], v[164:167], v[208:211], v[88:91]
	v_mfma_f32_16x16x32_bf16 v[84:87], v[172:175], v[208:211], v[84:87]
	v_mfma_f32_16x16x32_bf16 v[72:75], v[164:167], v[216:219], v[72:75]
	v_mfma_f32_16x16x32_bf16 v[68:71], v[172:175], v[216:219], v[68:71]
	s_setprio 0
	s_barrier
; #define PG8_STAGE(bufoff, gbase, voff) do { _Pragma("unroll") for (int _i = 0; _i < 2; ++_i) \
;         __builtin_amdgcn_global_load_lds((const unsigned*)((const char*)(gbase) + (voff)[_i]), (PG8_LAS unsigned*)(lds + (bufoff) + ldsw + _i * 8192), 16, 0, 0); } while (0)
; #define PG8_LDA(dst, b, h) do { _Pragma("unroll") for (int m = 0; m < 4; ++m) _Pragma("unroll") for (int k = 0; k < 2; ++k) dst[m][k] = *(const PG8_LAS bf16x8*)(lds + PG8_SA(b, h) + aoff + m * 2048 + k * 1024); } while (0)
; #define PG8_MMA(ai, bj, At, Bt) do { __builtin_amdgcn_s_setprio(1); _Pragma("unroll") for (int m = 0; m < 4; ++m) _Pragma("unroll") for (int n = 0; n < 2; ++n) _Pragma("unroll") for (int k = 0; k < 2; ++k) \
;         acc[ai][bj][m][n] = __builtin_amdgcn_mfma_f32_16x16x32_bf16(Bt[n][k], At[m][k], acc[ai][bj][m][n], 0, 0, 0); __builtin_amdgcn_s_setprio(0); } while (0)
; #define PG8_WAIT_V(n) asm volatile("s_waitcnt vmcnt(" #n ")" ::: "memory")
; #define PG8_WAIT_L(n) asm volatile("s_waitcnt lgkmcnt(" #n ")" ::: "memory")
; #define PG8_BAR __builtin_amdgcn_s_barrier()
; #define PG8_SCHED __builtin_amdgcn_sched_barrier(0)
; template <class Epi, class Sched, bool ALIGN_EPI = false, bool SP2 = false>
; __device__ __forceinline__ void gemm_phase(PG8_LAS unsigned char* lds, const Gemm g, const Sched& S, const Epi& E) {
;     ...
;             PG8_LDA(At, 1, 1); PG8_STAGE(PG8_SB(1, 0), b3, voffB); PG8_STAGE(PG8_SB(1, 1), b3 + hstep, voffB); PG8_STAGE(PG8_SA(1, 0), a3, voffA);
;             PG8_WAIT_V(8); PG8_WAIT_L(0); PG8_BAR; PG8_MMA(1, 0, At, B0); PG8_MMA(1, 1, At, B1); PG8_BAR; PG8_SCHED;
;     ...
;         if (!has_next) break;
; #pragma unroll
;         for (int a = 0; a < 2; ++a)
; #pragma unroll
;             for (int b = 0; b < 2; ++b)
; #pragma unroll
;                 for (int m = 0; m < 4; ++m)
; #pragma unroll
;                     for (int n = 0; n < 2; ++n) acc[a][b][m][n] = (f32x4){0.f, 0.f, 0.f, 0.f};
;         cur = nxt; cA = nA; cB = nB; ++ui;
	s_add_i32 s46, s69, s45
	v_lshl_add_u64 v[220:221], v[220:221], 0, s[8:9]
	s_mov_b32 m0, s46
	ds_read_b128 v[176:179], v107 offset:49152
	ds_read_b128 v[180:183], v107 offset:50176
	ds_read_b128 v[184:187], v107 offset:51200
	ds_read_b128 v[188:191], v107 offset:52224
	ds_read_b128 v[204:207], v107 offset:53248
	ds_read_b128 v[208:211], v107 offset:54272
	ds_read_b128 v[212:215], v107 offset:55296
	ds_read_b128 v[216:219], v107 offset:56320
	global_load_lds_dwordx4 v[220:221], off
	v_lshl_add_u64 v[220:221], v[222:223], 0, s[8:9]
	s_add_i32 m0, s46, 0x2000
	s_add_i32 s46, s70, s45
	global_load_lds_dwordx4 v[220:221], off
	v_lshl_add_u64 v[220:221], v[224:225], 0, s[8:9]
	s_mov_b32 m0, s46
	s_nop 0
	global_load_lds_dwordx4 v[220:221], off
	v_lshl_add_u64 v[220:221], v[226:227], 0, s[8:9]
	s_add_i32 m0, s46, 0x2000
	s_nop 0
	global_load_lds_dwordx4 v[220:221], off
	v_lshl_add_u64 v[220:221], v[238:239], 0, s[8:9]
	s_mov_b32 m0, s60
	s_nop 0
	global_load_lds_dwordx4 v[220:221], off
	v_lshl_add_u64 v[220:221], v[240:241], 0, s[8:9]
	s_mov_b32 m0, s61
	s_nop 0
	global_load_lds_dwordx4 v[220:221], off
	s_waitcnt vmcnt(8)
	s_waitcnt lgkmcnt(0)
	s_barrier
	s_setprio 1
	s_waitcnt lgkmcnt(0)
	v_mfma_f32_16x16x32_bf16 v[64:67], v[116:119], v[176:179], v[64:67]
	v_mfma_f32_16x16x32_bf16 v[60:63], v[152:155], v[176:179], v[60:63]
	v_mfma_f32_16x16x32_bf16 v[48:51], v[116:119], v[184:187], v[48:51]
	v_mfma_f32_16x16x32_bf16 v[44:47], v[152:155], v[184:187], v[44:47]
	v_mfma_f32_16x16x32_bf16 v[28:31], v[116:119], v[204:207], v[28:31]
	v_mfma_f32_16x16x32_bf16 v[24:27], v[152:155], v[204:207], v[24:27]
	v_mfma_f32_16x16x32_bf16 v[12:15], v[116:119], v[212:215], v[12:15]
	v_mfma_f32_16x16x32_bf16 v[8:11], v[152:155], v[212:215], v[8:11]
	v_mfma_f32_16x16x32_bf16 v[64:67], v[148:151], v[180:183], v[64:67]
	v_mfma_f32_16x16x32_bf16 v[60:63], v[156:159], v[180:183], v[60:63]
	v_mfma_f32_16x16x32_bf16 v[48:51], v[148:151], v[188:191], v[48:51]
	v_mfma_f32_16x16x32_bf16 v[44:47], v[156:159], v[188:191], v[44:47]
	v_mfma_f32_16x16x32_bf16 v[28:31], v[148:151], v[208:211], v[28:31]
	v_mfma_f32_16x16x32_bf16 v[24:27], v[156:159], v[208:211], v[24:27]
	v_mfma_f32_16x16x32_bf16 v[12:15], v[148:151], v[216:219], v[12:15]
	v_mfma_f32_16x16x32_bf16 v[8:11], v[156:159], v[216:219], v[8:11]
	v_mfma_f32_16x16x32_bf16 v[56:59], v[160:163], v[176:179], v[56:59]
	v_mfma_f32_16x16x32_bf16 v[52:55], v[168:171], v[176:179], v[52:55]
	v_mfma_f32_16x16x32_bf16 v[40:43], v[160:163], v[184:187], v[40:43]
	v_mfma_f32_16x16x32_bf16 v[36:39], v[168:171], v[184:187], v[36:39]
	v_mfma_f32_16x16x32_bf16 v[20:23], v[160:163], v[204:207], v[20:23]
	v_mfma_f32_16x16x32_bf16 v[16:19], v[168:171], v[204:207], v[16:19]
	v_mfma_f32_16x16x32_bf16 v[4:7], v[160:163], v[212:215], v[4:7]
	v_mfma_f32_16x16x32_bf16 v[0:3], v[168:171], v[212:215], v[0:3]
	v_mfma_f32_16x16x32_bf16 v[56:59], v[164:167], v[180:183], v[56:59]
	v_mfma_f32_16x16x32_bf16 v[52:55], v[172:175], v[180:183], v[52:55]
	v_mfma_f32_16x16x32_bf16 v[40:43], v[164:167], v[188:191], v[40:43]
	v_mfma_f32_16x16x32_bf16 v[36:39], v[172:175], v[188:191], v[36:39]
	v_mfma_f32_16x16x32_bf16 v[20:23], v[164:167], v[208:211], v[20:23]
	v_mfma_f32_16x16x32_bf16 v[16:19], v[172:175], v[208:211], v[16:19]
	v_mfma_f32_16x16x32_bf16 v[4:7], v[164:167], v[216:219], v[4:7]
	v_mfma_f32_16x16x32_bf16 v[0:3], v[172:175], v[216:219], v[0:3]
	s_setprio 0
	s_barrier
	s_add_u32 vcc_lo, vcc_lo, 0x100
	s_addc_u32 vcc_hi, vcc_hi, 0
	v_lshl_add_u64 v[104:105], v[104:105], 0, s[10:11]
	v_lshl_add_u64 v[34:35], v[34:35], 0, s[10:11]
	s_cmp_ge_u32 s68, s62
	s_mov_b32 s46, s68
	s_cbranch_scc0 .LBB0_826
	s_andn2_b64 vcc, exec, s[42:43]
	s_cbranch_vccnz .LBB0_818
	v_mov_b32_e32 v0, 0
	s_mov_b32 s24, s34
	s_mov_b32 s18, s36
	s_mov_b64 s[6:7], s[50:51]
	s_mov_b64 s[30:31], s[90:91]
	s_mov_b32 s64, s65
	v_mov_b32_e32 v1, v0
	v_mov_b32_e32 v2, v0
	v_mov_b32_e32 v3, v0
	v_mov_b32_e32 v4, v0
	v_mov_b32_e32 v5, v0
	v_mov_b32_e32 v6, v0
	v_mov_b32_e32 v7, v0
	v_mov_b32_e32 v16, v0
	v_mov_b32_e32 v17, v0
	v_mov_b32_e32 v18, v0
	v_mov_b32_e32 v19, v0
	v_mov_b32_e32 v20, v0
	v_mov_b32_e32 v21, v0
	v_mov_b32_e32 v22, v0
	v_mov_b32_e32 v23, v0
	v_mov_b32_e32 v36, v0
	v_mov_b32_e32 v37, v0
	v_mov_b32_e32 v38, v0
	v_mov_b32_e32 v39, v0
	v_mov_b32_e32 v40, v0
	v_mov_b32_e32 v41, v0
	v_mov_b32_e32 v42, v0
	v_mov_b32_e32 v43, v0
	v_mov_b32_e32 v52, v0
	v_mov_b32_e32 v53, v0
	v_mov_b32_e32 v54, v0
	v_mov_b32_e32 v55, v0
	v_mov_b32_e32 v56, v0
	v_mov_b32_e32 v57, v0
	v_mov_b32_e32 v58, v0
	v_mov_b32_e32 v59, v0
	v_mov_b32_e32 v8, v0
	v_mov_b32_e32 v9, v0
	v_mov_b32_e32 v10, v0
	v_mov_b32_e32 v11, v0
	v_mov_b32_e32 v12, v0
	v_mov_b32_e32 v13, v0
	v_mov_b32_e32 v14, v0
	v_mov_b32_e32 v15, v0
	v_mov_b32_e32 v24, v0
	v_mov_b32_e32 v25, v0
	v_mov_b32_e32 v26, v0
	v_mov_b32_e32 v27, v0
	v_mov_b32_e32 v28, v0
	v_mov_b32_e32 v29, v0
	v_mov_b32_e32 v30, v0
	v_mov_b32_e32 v31, v0
	v_mov_b32_e32 v44, v0
	v_mov_b32_e32 v45, v0
	v_mov_b32_e32 v46, v0
	v_mov_b32_e32 v47, v0
	v_mov_b32_e32 v48, v0
	v_mov_b32_e32 v49, v0
	v_mov_b32_e32 v50, v0
	v_mov_b32_e32 v51, v0
	v_mov_b32_e32 v60, v0
	v_mov_b32_e32 v61, v0
	v_mov_b32_e32 v62, v0
	v_mov_b32_e32 v63, v0
	v_mov_b32_e32 v64, v0
	v_mov_b32_e32 v65, v0
	v_mov_b32_e32 v66, v0
	v_mov_b32_e32 v67, v0
	v_mov_b32_e32 v68, v0
	v_mov_b32_e32 v69, v0
	v_mov_b32_e32 v70, v0
	v_mov_b32_e32 v71, v0
	v_mov_b32_e32 v72, v0
	v_mov_b32_e32 v73, v0
	v_mov_b32_e32 v74, v0
	v_mov_b32_e32 v75, v0
	v_mov_b32_e32 v84, v0
	v_mov_b32_e32 v85, v0
	v_mov_b32_e32 v86, v0
	v_mov_b32_e32 v87, v0
	v_mov_b32_e32 v88, v0
	v_mov_b32_e32 v89, v0
	v_mov_b32_e32 v90, v0
	v_mov_b32_e32 v91, v0
	v_mov_b32_e32 v112, v0
	v_mov_b32_e32 v113, v0
	v_mov_b32_e32 v114, v0
	v_mov_b32_e32 v115, v0
	v_mov_b32_e32 v120, v0
	v_mov_b32_e32 v121, v0
	v_mov_b32_e32 v122, v0
	v_mov_b32_e32 v123, v0
	v_mov_b32_e32 v132, v0
	v_mov_b32_e32 v133, v0
	v_mov_b32_e32 v134, v0
	v_mov_b32_e32 v135, v0
	v_mov_b32_e32 v136, v0
	v_mov_b32_e32 v137, v0
	v_mov_b32_e32 v138, v0
	v_mov_b32_e32 v139, v0
	v_mov_b32_e32 v76, v0
	v_mov_b32_e32 v77, v0
	v_mov_b32_e32 v78, v0
	v_mov_b32_e32 v79, v0
	v_mov_b32_e32 v80, v0
	v_mov_b32_e32 v81, v0
	v_mov_b32_e32 v82, v0
	v_mov_b32_e32 v83, v0
	v_mov_b32_e32 v96, v0
	v_mov_b32_e32 v97, v0
	v_mov_b32_e32 v98, v0
	v_mov_b32_e32 v99, v0
	v_mov_b32_e32 v108, v0
	v_mov_b32_e32 v109, v0
	v_mov_b32_e32 v110, v0
	v_mov_b32_e32 v111, v0
	v_mov_b32_e32 v124, v0
	v_mov_b32_e32 v125, v0
	v_mov_b32_e32 v126, v0
	v_mov_b32_e32 v127, v0
	v_mov_b32_e32 v128, v0
	v_mov_b32_e32 v129, v0
	v_mov_b32_e32 v130, v0
	v_mov_b32_e32 v131, v0
	v_mov_b32_e32 v140, v0
	v_mov_b32_e32 v141, v0
	v_mov_b32_e32 v142, v0
	v_mov_b32_e32 v143, v0
	v_mov_b32_e32 v144, v0
	v_mov_b32_e32 v145, v0
	v_mov_b32_e32 v146, v0
	v_mov_b32_e32 v147, v0
	s_branch .LBB0_818

; #define PG8_STAGE(bufoff, gbase, voff) do { _Pragma("unroll") for (int _i = 0; _i < 2; ++_i) \
;         __builtin_amdgcn_global_load_lds((const unsigned*)((const char*)(gbase) + (voff)[_i]), (PG8_LAS unsigned*)(lds + (bufoff) + ldsw + _i * 8192), 16, 0, 0); } while (0)
; #define PG8_LDA(dst, b, h) do { _Pragma("unroll") for (int m = 0; m < 4; ++m) _Pragma("unroll") for (int k = 0; k < 2; ++k) dst[m][k] = *(const PG8_LAS bf16x8*)(lds + PG8_SA(b, h) + aoff + m * 2048 + k * 1024); } while (0)
; #define PG8_LDB(dst, b, h) do { _Pragma("unroll") for (int n = 0; n < 2; ++n) _Pragma("unroll") for (int k = 0; k < 2; ++k) dst[n][k] = *(const PG8_LAS bf16x8*)(lds + PG8_SB(b, h) + boff + n * 2048 + k * 1024); } while (0)
; #define PG8_MMA(ai, bj, At, Bt) do { __builtin_amdgcn_s_setprio(1); _Pragma("unroll") for (int m = 0; m < 4; ++m) _Pragma("unroll") for (int n = 0; n < 2; ++n) _Pragma("unroll") for (int k = 0; k < 2; ++k) \
;         acc[ai][bj][m][n] = __builtin_amdgcn_mfma_f32_16x16x32_bf16(Bt[n][k], At[m][k], acc[ai][bj][m][n], 0, 0, 0); __builtin_amdgcn_s_setprio(0); } while (0)
; #define PG8_BAR __builtin_amdgcn_s_barrier()
; template <class Epi, class Sched, bool ALIGN_EPI = false, bool SP2 = false>
; __device__ __forceinline__ void gemm_phase(PG8_LAS unsigned char* lds, const Gemm g, const Sched& S, const Epi& E) {
;     ...
;         const bool has_next = S.next(ui + 1, nxt);
;         const char* nA = has_next ? (const char*)g.A + (size_t)nxt.pm * tstep : cA; const char* nB = has_next ? (const char*)g.Bt + (size_t)nxt.pn * tstep : cB;
;         for (int t = 0; t < nt; t += 2) {
;             const bool last = (t == nt - 2);
;             const char* a1 = cA + (size_t)(t + 1) * kstep;
;             const char* a2 = last ? nA : cA + (size_t)(t + 2) * kstep; const char* b2 = last ? nB : cB + (size_t)(t + 2) * kstep;
;             const char* a3 = a2 + kstep; const char* b3 = b2 + kstep;
;             if (last && has_next) S.a_ready(nxt);
;             if constexpr (SP2) {
;             PG8_LDB(B0, 0, 0); PG8_LDB(B1, 0, 1); PG8_SCHED; PG8_LDA(At, 0, 0); PG8_STAGE(PG8_SA(1, 1), a1 + hstep, voffA);
;             PG8_WAIT_V(8); PG8_WAIT_L(0); PG8_BAR; PG8_MMA(0, 0, At, B0); PG8_MMA(0, 1, At, B1); PG8_BAR; PG8_SCHED;
;             PG8_LDA(At, 0, 1); PG8_STAGE(PG8_SB(0, 0), b2, voffB); PG8_STAGE(PG8_SB(0, 1), b2 + hstep, voffB); PG8_STAGE(PG8_SA(0, 0), a2, voffA);
.LBB0_936:
	s_add_u32 s42, s36, 0xfffc0080
	s_addc_u32 s43, s37, -1
	s_add_i32 s64, 0, 0x10000
	s_cmp_eq_u32 s63, 12
	s_cselect_b32 s47, s27, s43
	s_cselect_b32 s46, s59, s42
	v_add_u32_e32 v145, s64, v142
	s_cselect_b32 s43, s25, s62
	s_cselect_b32 s42, s60, s61
	s_add_i32 s66, 0, 0x14000
	ds_read_b128 v[146:149], v145
	ds_read_b128 v[150:153], v145 offset:1024
	ds_read_b128 v[154:157], v145 offset:2048
	ds_read_b128 v[158:161], v145 offset:3072
	v_add_u32_e32 v145, s66, v142
	ds_read_b128 v[162:165], v145
	ds_read_b128 v[166:169], v145 offset:1024
	ds_read_b128 v[170:173], v145 offset:2048
	ds_read_b128 v[174:177], v145 offset:3072
	v_lshl_add_u64 v[220:221], s[36:37], 0, v[138:139]
	s_add_i32 m0, s51, 0xc000
	ds_read_b128 v[178:181], v144
	ds_read_b128 v[182:185], v144 offset:1024
	ds_read_b128 v[186:189], v144 offset:2048
	ds_read_b128 v[190:193], v144 offset:3072
	ds_read_b128 v[204:207], v144 offset:4096
	ds_read_b128 v[208:211], v144 offset:5120
	ds_read_b128 v[212:215], v144 offset:6144
	ds_read_b128 v[216:219], v144 offset:7168
	global_load_lds_dwordx4 v[220:221], off
	v_lshl_add_u64 v[220:221], s[36:37], 0, v[140:141]
	s_add_i32 m0, s51, 0xe000
	s_nop 0
	global_load_lds_dwordx4 v[220:221], off
	s_waitcnt vmcnt(8)
	s_waitcnt lgkmcnt(0)
	s_barrier
	s_setprio 1
	s_waitcnt lgkmcnt(0)
	v_mfma_f32_16x16x32_bf16 v[126:129], v[146:149], v[178:181], v[126:129]
	v_mfma_f32_16x16x32_bf16 v[122:125], v[154:157], v[178:181], v[122:125]
	v_mfma_f32_16x16x32_bf16 v[110:113], v[146:149], v[186:189], v[110:113]
	v_mfma_f32_16x16x32_bf16 v[106:109], v[154:157], v[186:189], v[106:109]
	v_mfma_f32_16x16x32_bf16 v[94:97], v[146:149], v[204:207], v[94:97]
	v_mfma_f32_16x16x32_bf16 v[90:93], v[154:157], v[204:207], v[90:93]
	v_mfma_f32_16x16x32_bf16 v[78:81], v[146:149], v[212:215], v[78:81]
	v_mfma_f32_16x16x32_bf16 v[74:77], v[154:157], v[212:215], v[74:77]
	v_mfma_f32_16x16x32_bf16 v[126:129], v[150:153], v[182:185], v[126:129]
	v_mfma_f32_16x16x32_bf16 v[122:125], v[158:161], v[182:185], v[122:125]
	v_mfma_f32_16x16x32_bf16 v[110:113], v[150:153], v[190:193], v[110:113]
	v_mfma_f32_16x16x32_bf16 v[106:109], v[158:161], v[190:193], v[106:109]
	v_mfma_f32_16x16x32_bf16 v[94:97], v[150:153], v[208:211], v[94:97]
	v_mfma_f32_16x16x32_bf16 v[90:93], v[158:161], v[208:211], v[90:93]
	v_mfma_f32_16x16x32_bf16 v[78:81], v[150:153], v[216:219], v[78:81]
	v_mfma_f32_16x16x32_bf16 v[74:77], v[158:161], v[216:219], v[74:77]
	v_mfma_f32_16x16x32_bf16 v[118:121], v[162:165], v[178:181], v[118:121]
	v_mfma_f32_16x16x32_bf16 v[114:117], v[170:173], v[178:181], v[114:117]
	v_mfma_f32_16x16x32_bf16 v[102:105], v[162:165], v[186:189], v[102:105]
	v_mfma_f32_16x16x32_bf16 v[98:101], v[170:173], v[186:189], v[98:101]
	v_mfma_f32_16x16x32_bf16 v[86:89], v[162:165], v[204:207], v[86:89]
	v_mfma_f32_16x16x32_bf16 v[82:85], v[170:173], v[204:207], v[82:85]
	v_mfma_f32_16x16x32_bf16 v[70:73], v[162:165], v[212:215], v[70:73]
	v_mfma_f32_16x16x32_bf16 v[66:69], v[170:173], v[212:215], v[66:69]
	v_mfma_f32_16x16x32_bf16 v[118:121], v[166:169], v[182:185], v[118:121]
	v_mfma_f32_16x16x32_bf16 v[114:117], v[174:177], v[182:185], v[114:117]
	v_mfma_f32_16x16x32_bf16 v[102:105], v[166:169], v[190:193], v[102:105]
	v_mfma_f32_16x16x32_bf16 v[98:101], v[174:177], v[190:193], v[98:101]
	v_mfma_f32_16x16x32_bf16 v[86:89], v[166:169], v[208:211], v[86:89]
	v_mfma_f32_16x16x32_bf16 v[82:85], v[174:177], v[208:211], v[82:85]
	v_mfma_f32_16x16x32_bf16 v[70:73], v[166:169], v[216:219], v[70:73]
	v_mfma_f32_16x16x32_bf16 v[66:69], v[174:177], v[216:219], v[66:69]
	s_setprio 0
	s_barrier
	s_add_i32 s64, s64, s49
	v_lshl_add_u64 v[220:221], s[42:43], 0, v[134:135]
	s_mov_b32 m0, s64
	ds_read_b128 v[178:181], v144 offset:16384
	ds_read_b128 v[182:185], v144 offset:17408
	ds_read_b128 v[186:189], v144 offset:18432
	ds_read_b128 v[190:193], v144 offset:19456
	ds_read_b128 v[204:207], v144 offset:20480
	ds_read_b128 v[208:211], v144 offset:21504
	ds_read_b128 v[212:215], v144 offset:22528
	ds_read_b128 v[216:219], v144 offset:23552
	global_load_lds_dwordx4 v[220:221], off
	s_add_i32 m0, s64, 0x2000
	s_add_u32 s64, s42, 0x40000
	v_lshl_add_u64 v[222:223], s[42:43], 0, v[130:131]
	s_addc_u32 s65, s43, 0
	s_add_i32 s66, s66, s49
	global_load_lds_dwordx4 v[222:223], off
	v_lshl_add_u64 v[224:225], s[64:65], 0, v[134:135]
	s_mov_b32 m0, s66
	v_lshl_add_u64 v[226:227], s[46:47], 0, v[132:133]
	global_load_lds_dwordx4 v[224:225], off
	v_lshl_add_u64 v[224:225], s[64:65], 0, v[130:131]
	s_add_i32 m0, s66, 0x2000
	s_nop 0
	global_load_lds_dwordx4 v[224:225], off
	v_lshl_add_u64 v[224:225], s[46:47], 0, v[136:137]
	s_mov_b32 m0, s51
	s_nop 0
	global_load_lds_dwordx4 v[224:225], off
	s_mov_b32 m0, s52
	s_nop 0
	global_load_lds_dwordx4 v[226:227], off
	s_waitcnt vmcnt(8)
	s_waitcnt lgkmcnt(0)
	s_barrier
; #define PG8_STAGE(bufoff, gbase, voff) do { _Pragma("unroll") for (int _i = 0; _i < 2; ++_i) \
;         __builtin_amdgcn_global_load_lds((const unsigned*)((const char*)(gbase) + (voff)[_i]), (PG8_LAS unsigned*)(lds + (bufoff) + ldsw + _i * 8192), 16, 0, 0); } while (0)
; #define PG8_LDA(dst, b, h) do { _Pragma("unroll") for (int m = 0; m < 4; ++m) _Pragma("unroll") for (int k = 0; k < 2; ++k) dst[m][k] = *(const PG8_LAS bf16x8*)(lds + PG8_SA(b, h) + aoff + m * 2048 + k * 1024); } while (0)
; #define PG8_LDB(dst, b, h) do { _Pragma("unroll") for (int n = 0; n < 2; ++n) _Pragma("unroll") for (int k = 0; k < 2; ++k) dst[n][k] = *(const PG8_LAS bf16x8*)(lds + PG8_SB(b, h) + boff + n * 2048 + k * 1024); } while (0)
; #define PG8_MMA(ai, bj, At, Bt) do { __builtin_amdgcn_s_setprio(1); _Pragma("unroll") for (int m = 0; m < 4; ++m) _Pragma("unroll") for (int n = 0; n < 2; ++n) _Pragma("unroll") for (int k = 0; k < 2; ++k) \
;         acc[ai][bj][m][n] = __builtin_amdgcn_mfma_f32_16x16x32_bf16(Bt[n][k], At[m][k], acc[ai][bj][m][n], 0, 0, 0); __builtin_amdgcn_s_setprio(0); } while (0)
; #define PG8_WAIT_V(n) asm volatile("s_waitcnt vmcnt(" #n ")" ::: "memory")
; #define PG8_WAIT_L(n) asm volatile("s_waitcnt lgkmcnt(" #n ")" ::: "memory")
; #define PG8_BAR __builtin_amdgcn_s_barrier()
; #define PG8_SCHED __builtin_amdgcn_sched_barrier(0)
; template <class Epi, class Sched, bool ALIGN_EPI = false, bool SP2 = false>
; __device__ __forceinline__ void gemm_phase(PG8_LAS unsigned char* lds, const Gemm g, const Sched& S, const Epi& E) {
;     ...
;             PG8_WAIT_V(8); PG8_WAIT_L(0); PG8_BAR; PG8_MMA(1, 0, At, B0); PG8_MMA(1, 1, At, B1); PG8_BAR; PG8_SCHED;
;             PG8_LDB(B0, 1, 0); PG8_LDB(B1, 1, 1); PG8_SCHED; PG8_LDA(At, 1, 0); PG8_STAGE(PG8_SA(0, 1), a2 + hstep, voffA);
;             PG8_WAIT_V(8); PG8_WAIT_L(0); PG8_BAR; PG8_MMA(0, 0, At, B0); PG8_MMA(0, 1, At, B1); PG8_BAR; PG8_SCHED;
	s_setprio 1
	s_waitcnt lgkmcnt(0)
	v_mfma_f32_16x16x32_bf16 v[62:65], v[146:149], v[178:181], v[62:65]
	v_mfma_f32_16x16x32_bf16 v[58:61], v[154:157], v[178:181], v[58:61]
	v_mfma_f32_16x16x32_bf16 v[46:49], v[146:149], v[186:189], v[46:49]
	v_mfma_f32_16x16x32_bf16 v[42:45], v[154:157], v[186:189], v[42:45]
	v_mfma_f32_16x16x32_bf16 v[28:31], v[146:149], v[204:207], v[28:31]
	v_mfma_f32_16x16x32_bf16 v[24:27], v[154:157], v[204:207], v[24:27]
	v_mfma_f32_16x16x32_bf16 v[12:15], v[146:149], v[212:215], v[12:15]
	v_mfma_f32_16x16x32_bf16 v[8:11], v[154:157], v[212:215], v[8:11]
	v_mfma_f32_16x16x32_bf16 v[62:65], v[150:153], v[182:185], v[62:65]
	v_mfma_f32_16x16x32_bf16 v[58:61], v[158:161], v[182:185], v[58:61]
	v_mfma_f32_16x16x32_bf16 v[46:49], v[150:153], v[190:193], v[46:49]
	v_mfma_f32_16x16x32_bf16 v[42:45], v[158:161], v[190:193], v[42:45]
	v_mfma_f32_16x16x32_bf16 v[28:31], v[150:153], v[208:211], v[28:31]
	v_mfma_f32_16x16x32_bf16 v[24:27], v[158:161], v[208:211], v[24:27]
	v_mfma_f32_16x16x32_bf16 v[12:15], v[150:153], v[216:219], v[12:15]
	v_mfma_f32_16x16x32_bf16 v[8:11], v[158:161], v[216:219], v[8:11]
	v_mfma_f32_16x16x32_bf16 v[54:57], v[162:165], v[178:181], v[54:57]
	v_mfma_f32_16x16x32_bf16 v[50:53], v[170:173], v[178:181], v[50:53]
	v_mfma_f32_16x16x32_bf16 v[38:41], v[162:165], v[186:189], v[38:41]
	v_mfma_f32_16x16x32_bf16 v[34:37], v[170:173], v[186:189], v[34:37]
	v_mfma_f32_16x16x32_bf16 v[20:23], v[162:165], v[204:207], v[20:23]
	v_mfma_f32_16x16x32_bf16 v[16:19], v[170:173], v[204:207], v[16:19]
	v_mfma_f32_16x16x32_bf16 v[4:7], v[162:165], v[212:215], v[4:7]
	v_mfma_f32_16x16x32_bf16 v[0:3], v[170:173], v[212:215], v[0:3]
	v_mfma_f32_16x16x32_bf16 v[54:57], v[166:169], v[182:185], v[54:57]
	v_mfma_f32_16x16x32_bf16 v[50:53], v[174:177], v[182:185], v[50:53]
	v_mfma_f32_16x16x32_bf16 v[38:41], v[166:169], v[190:193], v[38:41]
	v_mfma_f32_16x16x32_bf16 v[34:37], v[174:177], v[190:193], v[34:37]
	v_mfma_f32_16x16x32_bf16 v[20:23], v[166:169], v[208:211], v[20:23]
	v_mfma_f32_16x16x32_bf16 v[16:19], v[174:177], v[208:211], v[16:19]
	v_mfma_f32_16x16x32_bf16 v[4:7], v[166:169], v[216:219], v[4:7]
	v_mfma_f32_16x16x32_bf16 v[0:3], v[174:177], v[216:219], v[0:3]
	s_setprio 0
	s_barrier
	s_add_i32 s64, 0, 0x18000
	v_add_u32_e32 v145, s64, v142
	s_add_i32 s65, 0, 0x1c000
	ds_read_b128 v[146:149], v145
	ds_read_b128 v[150:153], v145 offset:1024
	ds_read_b128 v[154:157], v145 offset:2048
	ds_read_b128 v[158:161], v145 offset:3072
	v_add_u32_e32 v145, s65, v142
	ds_read_b128 v[162:165], v145
	ds_read_b128 v[166:169], v145 offset:1024
	ds_read_b128 v[170:173], v145 offset:2048
	ds_read_b128 v[174:177], v145 offset:3072
	s_add_u32 s46, s46, 0x40000
	s_addc_u32 s47, s47, 0
	s_mov_b32 m0, s53
	v_lshl_add_u64 v[238:239], s[46:47], 0, v[136:137]
	ds_read_b128 v[178:181], v144 offset:32768
	ds_read_b128 v[182:185], v144 offset:33792
	ds_read_b128 v[186:189], v144 offset:34816
	ds_read_b128 v[190:193], v144 offset:35840
	ds_read_b128 v[204:207], v144 offset:36864
	ds_read_b128 v[208:211], v144 offset:37888
	ds_read_b128 v[212:215], v144 offset:38912
	ds_read_b128 v[216:219], v144 offset:39936
	global_load_lds_dwordx4 v[238:239], off
	v_lshl_add_u64 v[238:239], s[46:47], 0, v[132:133]
	s_mov_b32 m0, s55
	s_nop 0
	global_load_lds_dwordx4 v[238:239], off
	s_waitcnt vmcnt(8)
	s_waitcnt lgkmcnt(0)
	s_barrier
	s_setprio 1
	s_waitcnt lgkmcnt(0)
	v_mfma_f32_16x16x32_bf16 v[126:129], v[146:149], v[178:181], v[126:129]
	v_mfma_f32_16x16x32_bf16 v[122:125], v[154:157], v[178:181], v[122:125]
	v_mfma_f32_16x16x32_bf16 v[110:113], v[146:149], v[186:189], v[110:113]
	v_mfma_f32_16x16x32_bf16 v[106:109], v[154:157], v[186:189], v[106:109]
	v_mfma_f32_16x16x32_bf16 v[94:97], v[146:149], v[204:207], v[94:97]
	v_mfma_f32_16x16x32_bf16 v[90:93], v[154:157], v[204:207], v[90:93]
	v_mfma_f32_16x16x32_bf16 v[78:81], v[146:149], v[212:215], v[78:81]
	v_mfma_f32_16x16x32_bf16 v[74:77], v[154:157], v[212:215], v[74:77]
	v_mfma_f32_16x16x32_bf16 v[126:129], v[150:153], v[182:185], v[126:129]
	v_mfma_f32_16x16x32_bf16 v[122:125], v[158:161], v[182:185], v[122:125]
	v_mfma_f32_16x16x32_bf16 v[110:113], v[150:153], v[190:193], v[110:113]
	v_mfma_f32_16x16x32_bf16 v[106:109], v[158:161], v[190:193], v[106:109]
	v_mfma_f32_16x16x32_bf16 v[94:97], v[150:153], v[208:211], v[94:97]
	v_mfma_f32_16x16x32_bf16 v[90:93], v[158:161], v[208:211], v[90:93]
	v_mfma_f32_16x16x32_bf16 v[78:81], v[150:153], v[216:219], v[78:81]
	v_mfma_f32_16x16x32_bf16 v[74:77], v[158:161], v[216:219], v[74:77]
	v_mfma_f32_16x16x32_bf16 v[118:121], v[162:165], v[178:181], v[118:121]
	v_mfma_f32_16x16x32_bf16 v[114:117], v[170:173], v[178:181], v[114:117]
	v_mfma_f32_16x16x32_bf16 v[102:105], v[162:165], v[186:189], v[102:105]
	v_mfma_f32_16x16x32_bf16 v[98:101], v[170:173], v[186:189], v[98:101]
	v_mfma_f32_16x16x32_bf16 v[86:89], v[162:165], v[204:207], v[86:89]
	v_mfma_f32_16x16x32_bf16 v[82:85], v[170:173], v[204:207], v[82:85]
	v_mfma_f32_16x16x32_bf16 v[70:73], v[162:165], v[212:215], v[70:73]
	v_mfma_f32_16x16x32_bf16 v[66:69], v[170:173], v[212:215], v[66:69]
	v_mfma_f32_16x16x32_bf16 v[118:121], v[166:169], v[182:185], v[118:121]
	v_mfma_f32_16x16x32_bf16 v[114:117], v[174:177], v[182:185], v[114:117]
	v_mfma_f32_16x16x32_bf16 v[102:105], v[166:169], v[190:193], v[102:105]
	v_mfma_f32_16x16x32_bf16 v[98:101], v[174:177], v[190:193], v[98:101]
	v_mfma_f32_16x16x32_bf16 v[86:89], v[166:169], v[208:211], v[86:89]
	v_mfma_f32_16x16x32_bf16 v[82:85], v[174:177], v[208:211], v[82:85]
	v_mfma_f32_16x16x32_bf16 v[70:73], v[166:169], v[216:219], v[70:73]
	v_mfma_f32_16x16x32_bf16 v[66:69], v[174:177], v[216:219], v[66:69]
	s_setprio 0
	s_barrier
; #define PG8_STAGE(bufoff, gbase, voff) do { _Pragma("unroll") for (int _i = 0; _i < 2; ++_i) \
;         __builtin_amdgcn_global_load_lds((const unsigned*)((const char*)(gbase) + (voff)[_i]), (PG8_LAS unsigned*)(lds + (bufoff) + ldsw + _i * 8192), 16, 0, 0); } while (0)
; #define PG8_LDA(dst, b, h) do { _Pragma("unroll") for (int m = 0; m < 4; ++m) _Pragma("unroll") for (int k = 0; k < 2; ++k) dst[m][k] = *(const PG8_LAS bf16x8*)(lds + PG8_SA(b, h) + aoff + m * 2048 + k * 1024); } while (0)
; #define PG8_MMA(ai, bj, At, Bt) do { __builtin_amdgcn_s_setprio(1); _Pragma("unroll") for (int m = 0; m < 4; ++m) _Pragma("unroll") for (int n = 0; n < 2; ++n) _Pragma("unroll") for (int k = 0; k < 2; ++k) \
;         acc[ai][bj][m][n] = __builtin_amdgcn_mfma_f32_16x16x32_bf16(Bt[n][k], At[m][k], acc[ai][bj][m][n], 0, 0, 0); __builtin_amdgcn_s_setprio(0); } while (0)
; #define PG8_WAIT_V(n) asm volatile("s_waitcnt vmcnt(" #n ")" ::: "memory")
; #define PG8_WAIT_L(n) asm volatile("s_waitcnt lgkmcnt(" #n ")" ::: "memory")
; #define PG8_BAR __builtin_amdgcn_s_barrier()
; #define PG8_SCHED __builtin_amdgcn_sched_barrier(0)
; template <class Epi, class Sched, bool ALIGN_EPI = false, bool SP2 = false>
; __device__ __forceinline__ void gemm_phase(PG8_LAS unsigned char* lds, const Gemm g, const Sched& S, const Epi& E) {
;     ...
;             PG8_LDA(At, 1, 1); PG8_STAGE(PG8_SB(1, 0), b3, voffB); PG8_STAGE(PG8_SB(1, 1), b3 + hstep, voffB); PG8_STAGE(PG8_SA(1, 0), a3, voffA);
;             PG8_WAIT_V(8); PG8_WAIT_L(0); PG8_BAR; PG8_MMA(1, 0, At, B0); PG8_MMA(1, 1, At, B1); PG8_BAR; PG8_SCHED;
	s_add_i32 s46, s64, s49
	v_lshl_add_u64 v[220:221], v[220:221], 0, s[8:9]
	s_mov_b32 m0, s46
	ds_read_b128 v[178:181], v144 offset:49152
	ds_read_b128 v[182:185], v144 offset:50176
	ds_read_b128 v[186:189], v144 offset:51200
	ds_read_b128 v[190:193], v144 offset:52224
	ds_read_b128 v[204:207], v144 offset:53248
	ds_read_b128 v[208:211], v144 offset:54272
	ds_read_b128 v[212:215], v144 offset:55296
	ds_read_b128 v[216:219], v144 offset:56320
	global_load_lds_dwordx4 v[220:221], off
	s_add_i32 m0, s46, 0x2000
	s_add_u32 s42, s42, 0x40080
	v_lshl_add_u64 v[220:221], v[222:223], 0, s[8:9]
	s_addc_u32 s43, s43, 0
	s_add_i32 s46, s65, s49
	global_load_lds_dwordx4 v[220:221], off
	v_lshl_add_u64 v[220:221], s[42:43], 0, v[134:135]
	s_mov_b32 m0, s46
	s_nop 0
	global_load_lds_dwordx4 v[220:221], off
	v_lshl_add_u64 v[220:221], s[42:43], 0, v[130:131]
	s_add_i32 m0, s46, 0x2000
	s_nop 0
	global_load_lds_dwordx4 v[220:221], off
	v_lshl_add_u64 v[220:221], v[224:225], 0, s[8:9]
	s_mov_b32 m0, s56
	s_nop 0
	global_load_lds_dwordx4 v[220:221], off
	v_lshl_add_u64 v[220:221], v[226:227], 0, s[8:9]
	s_mov_b32 m0, s57
	s_nop 0
	global_load_lds_dwordx4 v[220:221], off
	s_waitcnt vmcnt(8)
	s_waitcnt lgkmcnt(0)
	s_barrier
	s_setprio 1
	s_waitcnt lgkmcnt(0)
	v_mfma_f32_16x16x32_bf16 v[62:65], v[146:149], v[178:181], v[62:65]
	v_mfma_f32_16x16x32_bf16 v[58:61], v[154:157], v[178:181], v[58:61]
	v_mfma_f32_16x16x32_bf16 v[46:49], v[146:149], v[186:189], v[46:49]
	v_mfma_f32_16x16x32_bf16 v[42:45], v[154:157], v[186:189], v[42:45]
	v_mfma_f32_16x16x32_bf16 v[28:31], v[146:149], v[204:207], v[28:31]
	v_mfma_f32_16x16x32_bf16 v[24:27], v[154:157], v[204:207], v[24:27]
	v_mfma_f32_16x16x32_bf16 v[12:15], v[146:149], v[212:215], v[12:15]
	v_mfma_f32_16x16x32_bf16 v[8:11], v[154:157], v[212:215], v[8:11]
	v_mfma_f32_16x16x32_bf16 v[62:65], v[150:153], v[182:185], v[62:65]
	v_mfma_f32_16x16x32_bf16 v[58:61], v[158:161], v[182:185], v[58:61]
	v_mfma_f32_16x16x32_bf16 v[46:49], v[150:153], v[190:193], v[46:49]
	v_mfma_f32_16x16x32_bf16 v[42:45], v[158:161], v[190:193], v[42:45]
	v_mfma_f32_16x16x32_bf16 v[28:31], v[150:153], v[208:211], v[28:31]
	v_mfma_f32_16x16x32_bf16 v[24:27], v[158:161], v[208:211], v[24:27]
	v_mfma_f32_16x16x32_bf16 v[12:15], v[150:153], v[216:219], v[12:15]
	v_mfma_f32_16x16x32_bf16 v[8:11], v[158:161], v[216:219], v[8:11]
	v_mfma_f32_16x16x32_bf16 v[54:57], v[162:165], v[178:181], v[54:57]
	v_mfma_f32_16x16x32_bf16 v[50:53], v[170:173], v[178:181], v[50:53]
	v_mfma_f32_16x16x32_bf16 v[38:41], v[162:165], v[186:189], v[38:41]
	v_mfma_f32_16x16x32_bf16 v[34:37], v[170:173], v[186:189], v[34:37]
	v_mfma_f32_16x16x32_bf16 v[20:23], v[162:165], v[204:207], v[20:23]
	v_mfma_f32_16x16x32_bf16 v[16:19], v[170:173], v[204:207], v[16:19]
	v_mfma_f32_16x16x32_bf16 v[4:7], v[162:165], v[212:215], v[4:7]
	v_mfma_f32_16x16x32_bf16 v[0:3], v[170:173], v[212:215], v[0:3]
	v_mfma_f32_16x16x32_bf16 v[54:57], v[166:169], v[182:185], v[54:57]
	v_mfma_f32_16x16x32_bf16 v[50:53], v[174:177], v[182:185], v[50:53]
	v_mfma_f32_16x16x32_bf16 v[38:41], v[166:169], v[190:193], v[38:41]
	v_mfma_f32_16x16x32_bf16 v[34:37], v[174:177], v[190:193], v[34:37]
	v_mfma_f32_16x16x32_bf16 v[20:23], v[166:169], v[208:211], v[20:23]
	v_mfma_f32_16x16x32_bf16 v[16:19], v[174:177], v[208:211], v[16:19]
	v_mfma_f32_16x16x32_bf16 v[4:7], v[166:169], v[216:219], v[4:7]
	v_mfma_f32_16x16x32_bf16 v[0:3], v[174:177], v[216:219], v[0:3]
	s_setprio 0
	s_barrier
	s_add_i32 s63, s63, 2
	s_add_u32 s36, s36, 0x100
	s_addc_u32 s37, s37, 0
	s_add_u32 s61, s61, 0x100
	s_addc_u32 s62, s62, 0
	s_cmp_gt_u32 s63, 13
	s_cbranch_scc0 .LBB0_936
	s_and_b64 vcc, exec, s[22:23]
	s_cbranch_vccz .LBB0_939
	s_barrier

; #define PG8_STAGE(bufoff, gbase, voff) do { _Pragma("unroll") for (int _i = 0; _i < 2; ++_i) \
;         __builtin_amdgcn_global_load_lds((const unsigned*)((const char*)(gbase) + (voff)[_i]), (PG8_LAS unsigned*)(lds + (bufoff) + ldsw + _i * 8192), 16, 0, 0); } while (0)
; #define PG8_LDA(dst, b, h) do { _Pragma("unroll") for (int m = 0; m < 4; ++m) _Pragma("unroll") for (int k = 0; k < 2; ++k) dst[m][k] = *(const PG8_LAS bf16x8*)(lds + PG8_SA(b, h) + aoff + m * 2048 + k * 1024); } while (0)
; #define PG8_LDB(dst, b, h) do { _Pragma("unroll") for (int n = 0; n < 2; ++n) _Pragma("unroll") for (int k = 0; k < 2; ++k) dst[n][k] = *(const PG8_LAS bf16x8*)(lds + PG8_SB(b, h) + boff + n * 2048 + k * 1024); } while (0)
; #define PG8_MMA(ai, bj, At, Bt) do { __builtin_amdgcn_s_setprio(1); _Pragma("unroll") for (int m = 0; m < 4; ++m) _Pragma("unroll") for (int n = 0; n < 2; ++n) _Pragma("unroll") for (int k = 0; k < 2; ++k) \
;         acc[ai][bj][m][n] = __builtin_amdgcn_mfma_f32_16x16x32_bf16(Bt[n][k], At[m][k], acc[ai][bj][m][n], 0, 0, 0); __builtin_amdgcn_s_setprio(0); } while (0)
; #define PG8_BAR __builtin_amdgcn_s_barrier()
; template <class Epi, class Sched, bool ALIGN_EPI = false, bool SP2 = false>
; __device__ __forceinline__ void gemm_phase(PG8_LAS unsigned char* lds, const Gemm g, const Sched& S, const Epi& E) {
;     ...
;         const bool has_next = S.next(ui + 1, nxt);
;         const char* nA = has_next ? (const char*)g.A + (size_t)nxt.pm * tstep : cA; const char* nB = has_next ? (const char*)g.Bt + (size_t)nxt.pn * tstep : cB;
;         for (int t = 0; t < nt; t += 2) {
;             const bool last = (t == nt - 2);
;             const char* a1 = cA + (size_t)(t + 1) * kstep;
;             const char* a2 = last ? nA : cA + (size_t)(t + 2) * kstep; const char* b2 = last ? nB : cB + (size_t)(t + 2) * kstep;
;             const char* a3 = a2 + kstep; const char* b3 = b2 + kstep;
;             if (last && has_next) S.a_ready(nxt);
;             if constexpr (SP2) {
;             PG8_LDB(B0, 0, 0); PG8_LDB(B1, 0, 1); PG8_SCHED; PG8_LDA(At, 0, 0); PG8_STAGE(PG8_SA(1, 1), a1 + hstep, voffA);
;             PG8_WAIT_V(8); PG8_WAIT_L(0); PG8_BAR; PG8_MMA(0, 0, At, B0); PG8_MMA(0, 1, At, B1); PG8_BAR; PG8_SCHED;
;             PG8_LDA(At, 0, 1); PG8_STAGE(PG8_SB(0, 0), b2, voffB); PG8_STAGE(PG8_SB(0, 1), b2 + hstep, voffB); PG8_STAGE(PG8_SA(0, 0), a2, voffA);
.LBB0_1081:
	s_add_u32 s46, s6, s44
	s_addc_u32 s47, s7, s45
	s_add_u32 s46, s46, 0x100
	s_addc_u32 s47, s47, 0
	s_add_u32 s68, s66, s44
	s_addc_u32 s69, s67, s45
	s_add_i32 s70, 0, 0x10000
	s_cmpk_eq_i32 s44, 0x1500
	s_cselect_b32 s51, s37, s47
	s_cselect_b32 s50, s36, s46
	v_add_u32_e32 v33, s70, v142
	s_cselect_b32 s47, s35, s69
	s_cselect_b32 s46, s34, s68
	s_add_i32 s71, 0, 0x14000
	ds_read_b128 v[144:147], v33
	ds_read_b128 v[148:151], v33 offset:1024
	ds_read_b128 v[152:155], v33 offset:2048
	ds_read_b128 v[156:159], v33 offset:3072
	v_add_u32_e32 v33, s71, v142
	ds_read_b128 v[160:163], v33
	ds_read_b128 v[164:167], v33 offset:1024
	ds_read_b128 v[168:171], v33 offset:2048
	ds_read_b128 v[172:175], v33 offset:3072
	v_lshl_add_u64 v[220:221], v[34:35], 0, s[44:45]
	s_add_i32 m0, s56, 0xc000
	ds_read_b128 v[176:179], v143
	ds_read_b128 v[180:183], v143 offset:1024
	ds_read_b128 v[184:187], v143 offset:2048
	ds_read_b128 v[188:191], v143 offset:3072
	ds_read_b128 v[204:207], v143 offset:4096
	ds_read_b128 v[208:211], v143 offset:5120
	ds_read_b128 v[212:215], v143 offset:6144
	ds_read_b128 v[216:219], v143 offset:7168
	global_load_lds_dwordx4 v[220:221], off
	v_lshl_add_u64 v[220:221], v[140:141], 0, s[44:45]
	s_add_i32 m0, s56, 0xe000
	s_nop 0
	global_load_lds_dwordx4 v[220:221], off
	s_waitcnt vmcnt(8)
	s_waitcnt lgkmcnt(0)
	s_barrier
	s_setprio 1
	s_waitcnt lgkmcnt(0)
	v_mfma_f32_16x16x32_bf16 v[128:131], v[144:147], v[176:179], v[128:131]
	v_mfma_f32_16x16x32_bf16 v[124:127], v[152:155], v[176:179], v[124:127]
	v_mfma_f32_16x16x32_bf16 v[112:115], v[144:147], v[184:187], v[112:115]
	v_mfma_f32_16x16x32_bf16 v[108:111], v[152:155], v[184:187], v[108:111]
	v_mfma_f32_16x16x32_bf16 v[96:99], v[144:147], v[204:207], v[96:99]
	v_mfma_f32_16x16x32_bf16 v[92:95], v[152:155], v[204:207], v[92:95]
	v_mfma_f32_16x16x32_bf16 v[80:83], v[144:147], v[212:215], v[80:83]
	v_mfma_f32_16x16x32_bf16 v[76:79], v[152:155], v[212:215], v[76:79]
	v_mfma_f32_16x16x32_bf16 v[128:131], v[148:151], v[180:183], v[128:131]
	v_mfma_f32_16x16x32_bf16 v[124:127], v[156:159], v[180:183], v[124:127]
	v_mfma_f32_16x16x32_bf16 v[112:115], v[148:151], v[188:191], v[112:115]
	v_mfma_f32_16x16x32_bf16 v[108:111], v[156:159], v[188:191], v[108:111]
	v_mfma_f32_16x16x32_bf16 v[96:99], v[148:151], v[208:211], v[96:99]
	v_mfma_f32_16x16x32_bf16 v[92:95], v[156:159], v[208:211], v[92:95]
	v_mfma_f32_16x16x32_bf16 v[80:83], v[148:151], v[216:219], v[80:83]
	v_mfma_f32_16x16x32_bf16 v[76:79], v[156:159], v[216:219], v[76:79]
	v_mfma_f32_16x16x32_bf16 v[120:123], v[160:163], v[176:179], v[120:123]
	v_mfma_f32_16x16x32_bf16 v[116:119], v[168:171], v[176:179], v[116:119]
	v_mfma_f32_16x16x32_bf16 v[104:107], v[160:163], v[184:187], v[104:107]
	v_mfma_f32_16x16x32_bf16 v[100:103], v[168:171], v[184:187], v[100:103]
	v_mfma_f32_16x16x32_bf16 v[88:91], v[160:163], v[204:207], v[88:91]
	v_mfma_f32_16x16x32_bf16 v[84:87], v[168:171], v[204:207], v[84:87]
	v_mfma_f32_16x16x32_bf16 v[72:75], v[160:163], v[212:215], v[72:75]
	v_mfma_f32_16x16x32_bf16 v[68:71], v[168:171], v[212:215], v[68:71]
	v_mfma_f32_16x16x32_bf16 v[120:123], v[164:167], v[180:183], v[120:123]
	v_mfma_f32_16x16x32_bf16 v[116:119], v[172:175], v[180:183], v[116:119]
	v_mfma_f32_16x16x32_bf16 v[104:107], v[164:167], v[188:191], v[104:107]
	v_mfma_f32_16x16x32_bf16 v[100:103], v[172:175], v[188:191], v[100:103]
	v_mfma_f32_16x16x32_bf16 v[88:91], v[164:167], v[208:211], v[88:91]
	v_mfma_f32_16x16x32_bf16 v[84:87], v[172:175], v[208:211], v[84:87]
	v_mfma_f32_16x16x32_bf16 v[72:75], v[164:167], v[216:219], v[72:75]
	v_mfma_f32_16x16x32_bf16 v[68:71], v[172:175], v[216:219], v[68:71]
	s_setprio 0
	s_barrier
	s_add_i32 s68, s70, s55
	v_lshl_add_u64 v[220:221], s[46:47], 0, v[132:133]
	s_mov_b32 m0, s68
	ds_read_b128 v[176:179], v143 offset:16384
	ds_read_b128 v[180:183], v143 offset:17408
	ds_read_b128 v[184:187], v143 offset:18432
	ds_read_b128 v[188:191], v143 offset:19456
	ds_read_b128 v[204:207], v143 offset:20480
	ds_read_b128 v[208:211], v143 offset:21504
	ds_read_b128 v[212:215], v143 offset:22528
	ds_read_b128 v[216:219], v143 offset:23552
	global_load_lds_dwordx4 v[220:221], off
	s_add_i32 m0, s68, 0x2000
	s_add_u32 s68, s46, 0xb0000
	v_lshl_add_u64 v[222:223], s[46:47], 0, v[134:135]
	s_addc_u32 s69, s47, 0
	s_add_i32 s70, s71, s55
	global_load_lds_dwordx4 v[222:223], off
	v_lshl_add_u64 v[224:225], s[68:69], 0, v[132:133]
	s_mov_b32 m0, s70
	v_lshl_add_u64 v[226:227], s[50:51], 0, v[134:135]
	global_load_lds_dwordx4 v[224:225], off
	v_lshl_add_u64 v[224:225], s[68:69], 0, v[134:135]
	s_add_i32 m0, s70, 0x2000
	s_nop 0
	global_load_lds_dwordx4 v[224:225], off
	v_lshl_add_u64 v[224:225], s[50:51], 0, v[132:133]
	s_mov_b32 m0, s56
	s_nop 0
	global_load_lds_dwordx4 v[224:225], off
	s_mov_b32 m0, s57
	s_nop 0
	global_load_lds_dwordx4 v[226:227], off
	s_waitcnt vmcnt(8)
	s_waitcnt lgkmcnt(0)
	s_barrier
; #define PG8_STAGE(bufoff, gbase, voff) do { _Pragma("unroll") for (int _i = 0; _i < 2; ++_i) \
;         __builtin_amdgcn_global_load_lds((const unsigned*)((const char*)(gbase) + (voff)[_i]), (PG8_LAS unsigned*)(lds + (bufoff) + ldsw + _i * 8192), 16, 0, 0); } while (0)
; #define PG8_LDA(dst, b, h) do { _Pragma("unroll") for (int m = 0; m < 4; ++m) _Pragma("unroll") for (int k = 0; k < 2; ++k) dst[m][k] = *(const PG8_LAS bf16x8*)(lds + PG8_SA(b, h) + aoff + m * 2048 + k * 1024); } while (0)
; #define PG8_LDB(dst, b, h) do { _Pragma("unroll") for (int n = 0; n < 2; ++n) _Pragma("unroll") for (int k = 0; k < 2; ++k) dst[n][k] = *(const PG8_LAS bf16x8*)(lds + PG8_SB(b, h) + boff + n * 2048 + k * 1024); } while (0)
; #define PG8_MMA(ai, bj, At, Bt) do { __builtin_amdgcn_s_setprio(1); _Pragma("unroll") for (int m = 0; m < 4; ++m) _Pragma("unroll") for (int n = 0; n < 2; ++n) _Pragma("unroll") for (int k = 0; k < 2; ++k) \
;         acc[ai][bj][m][n] = __builtin_amdgcn_mfma_f32_16x16x32_bf16(Bt[n][k], At[m][k], acc[ai][bj][m][n], 0, 0, 0); __builtin_amdgcn_s_setprio(0); } while (0)
; #define PG8_WAIT_V(n) asm volatile("s_waitcnt vmcnt(" #n ")" ::: "memory")
; #define PG8_WAIT_L(n) asm volatile("s_waitcnt lgkmcnt(" #n ")" ::: "memory")
; #define PG8_BAR __builtin_amdgcn_s_barrier()
; #define PG8_SCHED __builtin_amdgcn_sched_barrier(0)
; template <class Epi, class Sched, bool ALIGN_EPI = false, bool SP2 = false>
; __device__ __forceinline__ void gemm_phase(PG8_LAS unsigned char* lds, const Gemm g, const Sched& S, const Epi& E) {
;     ...
;             PG8_WAIT_V(8); PG8_WAIT_L(0); PG8_BAR; PG8_MMA(1, 0, At, B0); PG8_MMA(1, 1, At, B1); PG8_BAR; PG8_SCHED;
;             PG8_LDB(B0, 1, 0); PG8_LDB(B1, 1, 1); PG8_SCHED; PG8_LDA(At, 1, 0); PG8_STAGE(PG8_SA(0, 1), a2 + hstep, voffA);
;             PG8_WAIT_V(8); PG8_WAIT_L(0); PG8_BAR; PG8_MMA(0, 0, At, B0); PG8_MMA(0, 1, At, B1); PG8_BAR; PG8_SCHED;
	s_setprio 1
	s_waitcnt lgkmcnt(0)
	v_mfma_f32_16x16x32_bf16 v[64:67], v[144:147], v[176:179], v[64:67]
	v_mfma_f32_16x16x32_bf16 v[60:63], v[152:155], v[176:179], v[60:63]
	v_mfma_f32_16x16x32_bf16 v[48:51], v[144:147], v[184:187], v[48:51]
	v_mfma_f32_16x16x32_bf16 v[44:47], v[152:155], v[184:187], v[44:47]
	v_mfma_f32_16x16x32_bf16 v[28:31], v[144:147], v[204:207], v[28:31]
	v_mfma_f32_16x16x32_bf16 v[24:27], v[152:155], v[204:207], v[24:27]
	v_mfma_f32_16x16x32_bf16 v[12:15], v[144:147], v[212:215], v[12:15]
	v_mfma_f32_16x16x32_bf16 v[8:11], v[152:155], v[212:215], v[8:11]
	v_mfma_f32_16x16x32_bf16 v[64:67], v[148:151], v[180:183], v[64:67]
	v_mfma_f32_16x16x32_bf16 v[60:63], v[156:159], v[180:183], v[60:63]
	v_mfma_f32_16x16x32_bf16 v[48:51], v[148:151], v[188:191], v[48:51]
	v_mfma_f32_16x16x32_bf16 v[44:47], v[156:159], v[188:191], v[44:47]
	v_mfma_f32_16x16x32_bf16 v[28:31], v[148:151], v[208:211], v[28:31]
	v_mfma_f32_16x16x32_bf16 v[24:27], v[156:159], v[208:211], v[24:27]
	v_mfma_f32_16x16x32_bf16 v[12:15], v[148:151], v[216:219], v[12:15]
	v_mfma_f32_16x16x32_bf16 v[8:11], v[156:159], v[216:219], v[8:11]
	v_mfma_f32_16x16x32_bf16 v[56:59], v[160:163], v[176:179], v[56:59]
	v_mfma_f32_16x16x32_bf16 v[52:55], v[168:171], v[176:179], v[52:55]
	v_mfma_f32_16x16x32_bf16 v[40:43], v[160:163], v[184:187], v[40:43]
	v_mfma_f32_16x16x32_bf16 v[36:39], v[168:171], v[184:187], v[36:39]
	v_mfma_f32_16x16x32_bf16 v[20:23], v[160:163], v[204:207], v[20:23]
	v_mfma_f32_16x16x32_bf16 v[16:19], v[168:171], v[204:207], v[16:19]
	v_mfma_f32_16x16x32_bf16 v[4:7], v[160:163], v[212:215], v[4:7]
	v_mfma_f32_16x16x32_bf16 v[0:3], v[168:171], v[212:215], v[0:3]
	v_mfma_f32_16x16x32_bf16 v[56:59], v[164:167], v[180:183], v[56:59]
	v_mfma_f32_16x16x32_bf16 v[52:55], v[172:175], v[180:183], v[52:55]
	v_mfma_f32_16x16x32_bf16 v[40:43], v[164:167], v[188:191], v[40:43]
	v_mfma_f32_16x16x32_bf16 v[36:39], v[172:175], v[188:191], v[36:39]
	v_mfma_f32_16x16x32_bf16 v[20:23], v[164:167], v[208:211], v[20:23]
	v_mfma_f32_16x16x32_bf16 v[16:19], v[172:175], v[208:211], v[16:19]
	v_mfma_f32_16x16x32_bf16 v[4:7], v[164:167], v[216:219], v[4:7]
	v_mfma_f32_16x16x32_bf16 v[0:3], v[172:175], v[216:219], v[0:3]
	s_setprio 0
	s_barrier
	s_add_i32 s68, 0, 0x18000
	v_add_u32_e32 v33, s68, v142
	s_add_i32 s69, 0, 0x1c000
	ds_read_b128 v[144:147], v33
	ds_read_b128 v[148:151], v33 offset:1024
	ds_read_b128 v[152:155], v33 offset:2048
	ds_read_b128 v[156:159], v33 offset:3072
	v_add_u32_e32 v33, s69, v142
	ds_read_b128 v[160:163], v33
	ds_read_b128 v[164:167], v33 offset:1024
	ds_read_b128 v[168:171], v33 offset:2048
	ds_read_b128 v[172:175], v33 offset:3072
	s_add_u32 s50, s50, 0xb0000
	s_addc_u32 s51, s51, 0
	s_mov_b32 m0, s58
	v_lshl_add_u64 v[238:239], s[50:51], 0, v[132:133]
	ds_read_b128 v[176:179], v143 offset:32768
	ds_read_b128 v[180:183], v143 offset:33792
	ds_read_b128 v[184:187], v143 offset:34816
	ds_read_b128 v[188:191], v143 offset:35840
	ds_read_b128 v[204:207], v143 offset:36864
	ds_read_b128 v[208:211], v143 offset:37888
	ds_read_b128 v[212:215], v143 offset:38912
	ds_read_b128 v[216:219], v143 offset:39936
	global_load_lds_dwordx4 v[238:239], off
	v_lshl_add_u64 v[238:239], s[50:51], 0, v[134:135]
	s_mov_b32 m0, s59
	s_nop 0
	global_load_lds_dwordx4 v[238:239], off
	s_waitcnt vmcnt(8)
	s_waitcnt lgkmcnt(0)
	s_barrier
	s_setprio 1
	s_waitcnt lgkmcnt(0)
	v_mfma_f32_16x16x32_bf16 v[128:131], v[144:147], v[176:179], v[128:131]
	v_mfma_f32_16x16x32_bf16 v[124:127], v[152:155], v[176:179], v[124:127]
	v_mfma_f32_16x16x32_bf16 v[112:115], v[144:147], v[184:187], v[112:115]
	v_mfma_f32_16x16x32_bf16 v[108:111], v[152:155], v[184:187], v[108:111]
	v_mfma_f32_16x16x32_bf16 v[96:99], v[144:147], v[204:207], v[96:99]
	v_mfma_f32_16x16x32_bf16 v[92:95], v[152:155], v[204:207], v[92:95]
	v_mfma_f32_16x16x32_bf16 v[80:83], v[144:147], v[212:215], v[80:83]
	v_mfma_f32_16x16x32_bf16 v[76:79], v[152:155], v[212:215], v[76:79]
	v_mfma_f32_16x16x32_bf16 v[128:131], v[148:151], v[180:183], v[128:131]
	v_mfma_f32_16x16x32_bf16 v[124:127], v[156:159], v[180:183], v[124:127]
	v_mfma_f32_16x16x32_bf16 v[112:115], v[148:151], v[188:191], v[112:115]
	v_mfma_f32_16x16x32_bf16 v[108:111], v[156:159], v[188:191], v[108:111]
	v_mfma_f32_16x16x32_bf16 v[96:99], v[148:151], v[208:211], v[96:99]
	v_mfma_f32_16x16x32_bf16 v[92:95], v[156:159], v[208:211], v[92:95]
	v_mfma_f32_16x16x32_bf16 v[80:83], v[148:151], v[216:219], v[80:83]
	v_mfma_f32_16x16x32_bf16 v[76:79], v[156:159], v[216:219], v[76:79]
	v_mfma_f32_16x16x32_bf16 v[120:123], v[160:163], v[176:179], v[120:123]
	v_mfma_f32_16x16x32_bf16 v[116:119], v[168:171], v[176:179], v[116:119]
	v_mfma_f32_16x16x32_bf16 v[104:107], v[160:163], v[184:187], v[104:107]
	v_mfma_f32_16x16x32_bf16 v[100:103], v[168:171], v[184:187], v[100:103]
	v_mfma_f32_16x16x32_bf16 v[88:91], v[160:163], v[204:207], v[88:91]
	v_mfma_f32_16x16x32_bf16 v[84:87], v[168:171], v[204:207], v[84:87]
	v_mfma_f32_16x16x32_bf16 v[72:75], v[160:163], v[212:215], v[72:75]
	v_mfma_f32_16x16x32_bf16 v[68:71], v[168:171], v[212:215], v[68:71]
	v_mfma_f32_16x16x32_bf16 v[120:123], v[164:167], v[180:183], v[120:123]
	v_mfma_f32_16x16x32_bf16 v[116:119], v[172:175], v[180:183], v[116:119]
	v_mfma_f32_16x16x32_bf16 v[104:107], v[164:167], v[188:191], v[104:107]
	v_mfma_f32_16x16x32_bf16 v[100:103], v[172:175], v[188:191], v[100:103]
	v_mfma_f32_16x16x32_bf16 v[88:91], v[164:167], v[208:211], v[88:91]
	v_mfma_f32_16x16x32_bf16 v[84:87], v[172:175], v[208:211], v[84:87]
	v_mfma_f32_16x16x32_bf16 v[72:75], v[164:167], v[216:219], v[72:75]
	v_mfma_f32_16x16x32_bf16 v[68:71], v[172:175], v[216:219], v[68:71]
	s_setprio 0
	s_barrier
; #define PG8_STAGE(bufoff, gbase, voff) do { _Pragma("unroll") for (int _i = 0; _i < 2; ++_i) \
;         __builtin_amdgcn_global_load_lds((const unsigned*)((const char*)(gbase) + (voff)[_i]), (PG8_LAS unsigned*)(lds + (bufoff) + ldsw + _i * 8192), 16, 0, 0); } while (0)
; #define PG8_LDA(dst, b, h) do { _Pragma("unroll") for (int m = 0; m < 4; ++m) _Pragma("unroll") for (int k = 0; k < 2; ++k) dst[m][k] = *(const PG8_LAS bf16x8*)(lds + PG8_SA(b, h) + aoff + m * 2048 + k * 1024); } while (0)
; #define PG8_MMA(ai, bj, At, Bt) do { __builtin_amdgcn_s_setprio(1); _Pragma("unroll") for (int m = 0; m < 4; ++m) _Pragma("unroll") for (int n = 0; n < 2; ++n) _Pragma("unroll") for (int k = 0; k < 2; ++k) \
;         acc[ai][bj][m][n] = __builtin_amdgcn_mfma_f32_16x16x32_bf16(Bt[n][k], At[m][k], acc[ai][bj][m][n], 0, 0, 0); __builtin_amdgcn_s_setprio(0); } while (0)
; #define PG8_WAIT_V(n) asm volatile("s_waitcnt vmcnt(" #n ")" ::: "memory")
; #define PG8_WAIT_L(n) asm volatile("s_waitcnt lgkmcnt(" #n ")" ::: "memory")
; #define PG8_BAR __builtin_amdgcn_s_barrier()
; #define PG8_SCHED __builtin_amdgcn_sched_barrier(0)
; template <class Epi, class Sched, bool ALIGN_EPI = false, bool SP2 = false>
; __device__ __forceinline__ void gemm_phase(PG8_LAS unsigned char* lds, const Gemm g, const Sched& S, const Epi& E) {
;     ...
;             PG8_LDA(At, 1, 1); PG8_STAGE(PG8_SB(1, 0), b3, voffB); PG8_STAGE(PG8_SB(1, 1), b3 + hstep, voffB); PG8_STAGE(PG8_SA(1, 0), a3, voffA);
;             PG8_WAIT_V(8); PG8_WAIT_L(0); PG8_BAR; PG8_MMA(1, 0, At, B0); PG8_MMA(1, 1, At, B1); PG8_BAR; PG8_SCHED;
;     ...
;         if (!has_next) break;
; #pragma unroll
;         for (int a = 0; a < 2; ++a)
; #pragma unroll
;             for (int b = 0; b < 2; ++b)
; #pragma unroll
;                 for (int m = 0; m < 4; ++m)
; #pragma unroll
;                     for (int n = 0; n < 2; ++n) acc[a][b][m][n] = (f32x4){0.f, 0.f, 0.f, 0.f};
;         cur = nxt; cA = nA; cB = nB; ++ui;
	s_add_i32 s50, s68, s55
	v_lshl_add_u64 v[220:221], v[220:221], 0, s[8:9]
	s_mov_b32 m0, s50
	ds_read_b128 v[176:179], v143 offset:49152
	ds_read_b128 v[180:183], v143 offset:50176
	ds_read_b128 v[184:187], v143 offset:51200
	ds_read_b128 v[188:191], v143 offset:52224
	ds_read_b128 v[204:207], v143 offset:53248
	ds_read_b128 v[208:211], v143 offset:54272
	ds_read_b128 v[212:215], v143 offset:55296
	ds_read_b128 v[216:219], v143 offset:56320
	global_load_lds_dwordx4 v[220:221], off
	s_add_i32 m0, s50, 0x2000
	s_add_u32 s46, s46, 0xb0080
	v_lshl_add_u64 v[220:221], v[222:223], 0, s[8:9]
	s_addc_u32 s47, s47, 0
	s_add_i32 s50, s69, s55
	global_load_lds_dwordx4 v[220:221], off
	v_lshl_add_u64 v[220:221], s[46:47], 0, v[132:133]
	s_mov_b32 m0, s50
	s_nop 0
	global_load_lds_dwordx4 v[220:221], off
	v_lshl_add_u64 v[220:221], s[46:47], 0, v[134:135]
	s_add_i32 m0, s50, 0x2000
	s_nop 0
	global_load_lds_dwordx4 v[220:221], off
	v_lshl_add_u64 v[220:221], v[224:225], 0, s[8:9]
	s_mov_b32 m0, s60
	s_nop 0
	global_load_lds_dwordx4 v[220:221], off
	v_lshl_add_u64 v[220:221], v[226:227], 0, s[8:9]
	s_mov_b32 m0, s61
	s_nop 0
	global_load_lds_dwordx4 v[220:221], off
	s_waitcnt vmcnt(8)
	s_waitcnt lgkmcnt(0)
	s_barrier
	s_setprio 1
	s_waitcnt lgkmcnt(0)
	v_mfma_f32_16x16x32_bf16 v[64:67], v[144:147], v[176:179], v[64:67]
	v_mfma_f32_16x16x32_bf16 v[60:63], v[152:155], v[176:179], v[60:63]
	v_mfma_f32_16x16x32_bf16 v[48:51], v[144:147], v[184:187], v[48:51]
	v_mfma_f32_16x16x32_bf16 v[44:47], v[152:155], v[184:187], v[44:47]
	v_mfma_f32_16x16x32_bf16 v[28:31], v[144:147], v[204:207], v[28:31]
	v_mfma_f32_16x16x32_bf16 v[24:27], v[152:155], v[204:207], v[24:27]
	v_mfma_f32_16x16x32_bf16 v[12:15], v[144:147], v[212:215], v[12:15]
	v_mfma_f32_16x16x32_bf16 v[8:11], v[152:155], v[212:215], v[8:11]
	v_mfma_f32_16x16x32_bf16 v[64:67], v[148:151], v[180:183], v[64:67]
	v_mfma_f32_16x16x32_bf16 v[60:63], v[156:159], v[180:183], v[60:63]
	v_mfma_f32_16x16x32_bf16 v[48:51], v[148:151], v[188:191], v[48:51]
	v_mfma_f32_16x16x32_bf16 v[44:47], v[156:159], v[188:191], v[44:47]
	v_mfma_f32_16x16x32_bf16 v[28:31], v[148:151], v[208:211], v[28:31]
	v_mfma_f32_16x16x32_bf16 v[24:27], v[156:159], v[208:211], v[24:27]
	v_mfma_f32_16x16x32_bf16 v[12:15], v[148:151], v[216:219], v[12:15]
	v_mfma_f32_16x16x32_bf16 v[8:11], v[156:159], v[216:219], v[8:11]
	v_mfma_f32_16x16x32_bf16 v[56:59], v[160:163], v[176:179], v[56:59]
	v_mfma_f32_16x16x32_bf16 v[52:55], v[168:171], v[176:179], v[52:55]
	v_mfma_f32_16x16x32_bf16 v[40:43], v[160:163], v[184:187], v[40:43]
	v_mfma_f32_16x16x32_bf16 v[36:39], v[168:171], v[184:187], v[36:39]
	v_mfma_f32_16x16x32_bf16 v[20:23], v[160:163], v[204:207], v[20:23]
	v_mfma_f32_16x16x32_bf16 v[16:19], v[168:171], v[204:207], v[16:19]
	v_mfma_f32_16x16x32_bf16 v[4:7], v[160:163], v[212:215], v[4:7]
	v_mfma_f32_16x16x32_bf16 v[0:3], v[168:171], v[212:215], v[0:3]
	v_mfma_f32_16x16x32_bf16 v[56:59], v[164:167], v[180:183], v[56:59]
	v_mfma_f32_16x16x32_bf16 v[52:55], v[172:175], v[180:183], v[52:55]
	v_mfma_f32_16x16x32_bf16 v[40:43], v[164:167], v[188:191], v[40:43]
	v_mfma_f32_16x16x32_bf16 v[36:39], v[172:175], v[188:191], v[36:39]
	v_mfma_f32_16x16x32_bf16 v[20:23], v[164:167], v[208:211], v[20:23]
	v_mfma_f32_16x16x32_bf16 v[16:19], v[172:175], v[208:211], v[16:19]
	v_mfma_f32_16x16x32_bf16 v[4:7], v[164:167], v[216:219], v[4:7]
	v_mfma_f32_16x16x32_bf16 v[0:3], v[172:175], v[216:219], v[0:3]
	s_setprio 0
	s_barrier
	s_add_i32 s94, s94, 2
	s_add_u32 s44, s44, 0x100
	s_addc_u32 s45, s45, 0
	s_cmp_gt_u32 s94, 41
	s_cbranch_scc0 .LBB0_1081
	s_add_u32 s44, s66, 0xffffff00
	s_addc_u32 s45, s67, -1
	s_and_b64 vcc, exec, s[42:43]
	s_cbranch_vccnz .LBB0_1084
	v_mov_b32_e32 v0, 0
	s_mov_b32 s28, s63
	s_mov_b32 s90, s64
	s_mov_b64 s[6:7], s[36:37]
	s_mov_b32 s62, s65
	v_mov_b32_e32 v1, v0
	v_mov_b32_e32 v2, v0
	v_mov_b32_e32 v3, v0
	v_mov_b32_e32 v4, v0
	v_mov_b32_e32 v5, v0
	v_mov_b32_e32 v6, v0
	v_mov_b32_e32 v7, v0
	v_mov_b32_e32 v16, v0
	v_mov_b32_e32 v17, v0
	v_mov_b32_e32 v18, v0
	v_mov_b32_e32 v19, v0
	v_mov_b32_e32 v20, v0
	v_mov_b32_e32 v21, v0
	v_mov_b32_e32 v22, v0
	v_mov_b32_e32 v23, v0
	v_mov_b32_e32 v36, v0
	v_mov_b32_e32 v37, v0
	v_mov_b32_e32 v38, v0
	v_mov_b32_e32 v39, v0
	v_mov_b32_e32 v40, v0
	v_mov_b32_e32 v41, v0
	v_mov_b32_e32 v42, v0
	v_mov_b32_e32 v43, v0
	v_mov_b32_e32 v52, v0
	v_mov_b32_e32 v53, v0
	v_mov_b32_e32 v54, v0
	v_mov_b32_e32 v55, v0
	v_mov_b32_e32 v56, v0
	v_mov_b32_e32 v57, v0
	v_mov_b32_e32 v58, v0
	v_mov_b32_e32 v59, v0
	v_mov_b32_e32 v8, v0
	v_mov_b32_e32 v9, v0
	v_mov_b32_e32 v10, v0
	v_mov_b32_e32 v11, v0
	v_mov_b32_e32 v12, v0
	v_mov_b32_e32 v13, v0
	v_mov_b32_e32 v14, v0
	v_mov_b32_e32 v15, v0
	v_mov_b32_e32 v24, v0
	v_mov_b32_e32 v25, v0
	v_mov_b32_e32 v26, v0
	v_mov_b32_e32 v27, v0
	v_mov_b32_e32 v28, v0
	v_mov_b32_e32 v29, v0
	v_mov_b32_e32 v30, v0
	v_mov_b32_e32 v31, v0
	v_mov_b32_e32 v44, v0
	v_mov_b32_e32 v45, v0
	v_mov_b32_e32 v46, v0
	v_mov_b32_e32 v47, v0
	v_mov_b32_e32 v48, v0
	v_mov_b32_e32 v49, v0
	v_mov_b32_e32 v50, v0
	v_mov_b32_e32 v51, v0
	v_mov_b32_e32 v60, v0
	v_mov_b32_e32 v61, v0
	v_mov_b32_e32 v62, v0
	v_mov_b32_e32 v63, v0
	v_mov_b32_e32 v64, v0
	v_mov_b32_e32 v65, v0
	v_mov_b32_e32 v66, v0
	v_mov_b32_e32 v67, v0
	v_mov_b32_e32 v68, v0
	v_mov_b32_e32 v69, v0
	v_mov_b32_e32 v70, v0
	v_mov_b32_e32 v71, v0
	v_mov_b32_e32 v72, v0
	v_mov_b32_e32 v73, v0
	v_mov_b32_e32 v74, v0
	v_mov_b32_e32 v75, v0
	v_mov_b32_e32 v84, v0
	v_mov_b32_e32 v85, v0
	v_mov_b32_e32 v86, v0
	v_mov_b32_e32 v87, v0
	v_mov_b32_e32 v88, v0
	v_mov_b32_e32 v89, v0
	v_mov_b32_e32 v90, v0
	v_mov_b32_e32 v91, v0
	v_mov_b32_e32 v100, v0
	v_mov_b32_e32 v101, v0
	v_mov_b32_e32 v102, v0
	v_mov_b32_e32 v103, v0
	v_mov_b32_e32 v104, v0
	v_mov_b32_e32 v105, v0
	v_mov_b32_e32 v106, v0
	v_mov_b32_e32 v107, v0
	v_mov_b32_e32 v116, v0
	v_mov_b32_e32 v117, v0
	v_mov_b32_e32 v118, v0
	v_mov_b32_e32 v119, v0
	v_mov_b32_e32 v120, v0
	v_mov_b32_e32 v121, v0
	v_mov_b32_e32 v122, v0
	v_mov_b32_e32 v123, v0
	v_mov_b32_e32 v76, v0
	v_mov_b32_e32 v77, v0
	v_mov_b32_e32 v78, v0
	v_mov_b32_e32 v79, v0
	v_mov_b32_e32 v80, v0
	v_mov_b32_e32 v81, v0
	v_mov_b32_e32 v82, v0
	v_mov_b32_e32 v83, v0
	v_mov_b32_e32 v92, v0
	v_mov_b32_e32 v93, v0
	v_mov_b32_e32 v94, v0
	v_mov_b32_e32 v95, v0
	v_mov_b32_e32 v96, v0
	v_mov_b32_e32 v97, v0
	v_mov_b32_e32 v98, v0
	v_mov_b32_e32 v99, v0
	v_mov_b32_e32 v108, v0
	v_mov_b32_e32 v109, v0
	v_mov_b32_e32 v110, v0
	v_mov_b32_e32 v111, v0
	v_mov_b32_e32 v112, v0
	v_mov_b32_e32 v113, v0
	v_mov_b32_e32 v114, v0
	v_mov_b32_e32 v115, v0
	v_mov_b32_e32 v124, v0
	v_mov_b32_e32 v125, v0
	v_mov_b32_e32 v126, v0
	v_mov_b32_e32 v127, v0
	v_mov_b32_e32 v128, v0
	v_mov_b32_e32 v129, v0
	v_mov_b32_e32 v130, v0
	v_mov_b32_e32 v131, v0
	s_andn2_b64 vcc, exec, s[40:41]
	s_cbranch_vccnz .LBB0_1085
	s_branch .LBB0_1086
